# adds attention P*V steps with V fragments read two steps ahead; first merge GEMM epilogue: 8 gate loads issued together
# speedup vs baseline: 1.0227x; 1.0010x over previous
; #define PG8_STAGE(bufoff, gbase, voff) do { _Pragma("unroll") for (int _i = 0; _i < 2; ++_i) \
;         __builtin_amdgcn_global_load_lds((const unsigned*)((const char*)(gbase) + (voff)[_i]), (PG8_LAS unsigned*)(lds + (bufoff) + ldsw + _i * 8192), 16, 0, 0); } while (0)
; #define PG8_LDA(dst, b, h) do { _Pragma("unroll") for (int m = 0; m < 4; ++m) _Pragma("unroll") for (int k = 0; k < 2; ++k) dst[m][k] = *(const PG8_LAS bf16x8*)(lds + PG8_SA(b, h) + aoff + m * 2048 + k * 1024); } while (0)
; #define PG8_LDB(dst, b, h) do { _Pragma("unroll") for (int n = 0; n < 2; ++n) _Pragma("unroll") for (int k = 0; k < 2; ++k) dst[n][k] = *(const PG8_LAS bf16x8*)(lds + PG8_SB(b, h) + boff + n * 2048 + k * 1024); } while (0)
; #define PG8_MMA(ai, bj, At, Bt) do { __builtin_amdgcn_s_setprio(1); _Pragma("unroll") for (int m = 0; m < 4; ++m) _Pragma("unroll") for (int n = 0; n < 2; ++n) _Pragma("unroll") for (int k = 0; k < 2; ++k) \
;         acc[ai][bj][m][n] = __builtin_amdgcn_mfma_f32_16x16x32_bf16(Bt[n][k], At[m][k], acc[ai][bj][m][n], 0, 0, 0); __builtin_amdgcn_s_setprio(0); } while (0)
; #define PG8_WAIT_V(n) asm volatile("s_waitcnt vmcnt(" #n ")" ::: "memory")
; #define PG8_WAIT_L(n) asm volatile("s_waitcnt lgkmcnt(" #n ")" ::: "memory")
; #define PG8_BAR __builtin_amdgcn_s_barrier()
; #define PG8_SCHED __builtin_amdgcn_sched_barrier(0)
; template <class Epi, class Sched, bool ALIGN_EPI = false, bool SP2 = false>
; __device__ __forceinline__ void gemm_phase(PG8_LAS unsigned char* lds, const Gemm g, const Sched& S, const Epi& E) {
;     ...
;             if constexpr (SP2) {
;             PG8_LDB(B0, 0, 0); PG8_LDB(B1, 0, 1); PG8_SCHED; PG8_LDA(At, 0, 0); PG8_STAGE(PG8_SA(1, 1), a1 + hstep, voffA);
;             PG8_WAIT_V(8); PG8_WAIT_L(0); PG8_BAR; PG8_MMA(0, 0, At, B0); PG8_MMA(0, 1, At, B1); PG8_BAR; PG8_SCHED;
;             PG8_LDA(At, 0, 1); PG8_STAGE(PG8_SB(0, 0), b2, voffB); PG8_STAGE(PG8_SB(0, 1), b2 + hstep, voffB); PG8_STAGE(PG8_SA(0, 0), a2, voffA);
;             PG8_WAIT_V(8); PG8_WAIT_L(0); PG8_BAR; PG8_MMA(1, 0, At, B0); PG8_MMA(1, 1, At, B1); PG8_BAR; PG8_SCHED;
.LBB0_136:
	s_add_u32 s18, s58, 0xfffe0080
	s_addc_u32 s19, s59, -1
	s_add_i32 s46, 0, 0x10000
	s_cmp_eq_u32 s79, 4
	s_cselect_b32 s63, s37, s19
	s_cselect_b32 s62, s73, s18
	s_cselect_b32 s19, s11, s78
	s_cselect_b32 s18, s84, s85
	s_add_i32 s76, 0, 0x14000
	v_add_u32_e32 v172, s46, v1
	v_add_u32_e32 v203, s76, v1
	ds_read_b128 v[160:163], v172
	ds_read_b128 v[164:167], v172 offset:1024
	ds_read_b128 v[168:171], v172 offset:2048
	ds_read_b128 v[172:175], v172 offset:3072
	ds_read_b128 v[176:179], v203
	ds_read_b128 v[180:183], v203 offset:1024
	ds_read_b128 v[184:187], v203 offset:2048
	ds_read_b128 v[204:207], v203 offset:3072
	v_lshl_add_u64 v[240:241], s[58:59], 0, v[156:157]
	s_add_i32 m0, s5, 0xc000
	ds_read_b128 v[208:211], v143
	ds_read_b128 v[212:215], v143 offset:1024
	ds_read_b128 v[216:219], v143 offset:2048
	ds_read_b128 v[220:223], v143 offset:3072
	ds_read_b128 v[224:227], v143 offset:4096
	ds_read_b128 v[228:231], v143 offset:5120
	ds_read_b128 v[232:235], v143 offset:6144
	ds_read_b128 v[236:239], v143 offset:7168
	global_load_lds_dwordx4 v[240:241], off
	v_lshl_add_u64 v[240:241], s[58:59], 0, v[158:159]
	s_add_i32 m0, s5, 0xe000
	s_nop 0
	global_load_lds_dwordx4 v[240:241], off
	s_waitcnt vmcnt(8)
	s_waitcnt lgkmcnt(0)
	s_barrier
	s_setprio 1
	s_waitcnt lgkmcnt(0)
	v_mfma_f32_16x16x32_bf16 v[126:129], v[160:163], v[208:211], v[126:129]
	v_mfma_f32_16x16x32_bf16 v[122:125], v[168:171], v[208:211], v[122:125]
	v_mfma_f32_16x16x32_bf16 v[110:113], v[160:163], v[216:219], v[110:113]
	v_mfma_f32_16x16x32_bf16 v[106:109], v[168:171], v[216:219], v[106:109]
	v_mfma_f32_16x16x32_bf16 v[94:97], v[160:163], v[224:227], v[94:97]
	v_mfma_f32_16x16x32_bf16 v[90:93], v[168:171], v[224:227], v[90:93]
	v_mfma_f32_16x16x32_bf16 v[78:81], v[160:163], v[232:235], v[78:81]
	v_mfma_f32_16x16x32_bf16 v[74:77], v[168:171], v[232:235], v[74:77]
	v_mfma_f32_16x16x32_bf16 v[126:129], v[164:167], v[212:215], v[126:129]
	v_mfma_f32_16x16x32_bf16 v[122:125], v[172:175], v[212:215], v[122:125]
	v_mfma_f32_16x16x32_bf16 v[110:113], v[164:167], v[220:223], v[110:113]
	v_mfma_f32_16x16x32_bf16 v[106:109], v[172:175], v[220:223], v[106:109]
	v_mfma_f32_16x16x32_bf16 v[94:97], v[164:167], v[228:231], v[94:97]
	v_mfma_f32_16x16x32_bf16 v[90:93], v[172:175], v[228:231], v[90:93]
	v_mfma_f32_16x16x32_bf16 v[78:81], v[164:167], v[236:239], v[78:81]
	v_mfma_f32_16x16x32_bf16 v[74:77], v[172:175], v[236:239], v[74:77]
	s_setprio 0
	s_setprio 1
	v_mfma_f32_16x16x32_bf16 v[118:121], v[176:179], v[208:211], v[118:121]
	v_mfma_f32_16x16x32_bf16 v[114:117], v[184:187], v[208:211], v[114:117]
	v_mfma_f32_16x16x32_bf16 v[102:105], v[176:179], v[216:219], v[102:105]
	v_mfma_f32_16x16x32_bf16 v[98:101], v[184:187], v[216:219], v[98:101]
	v_mfma_f32_16x16x32_bf16 v[86:89], v[176:179], v[224:227], v[86:89]
	v_mfma_f32_16x16x32_bf16 v[82:85], v[184:187], v[224:227], v[82:85]
	v_mfma_f32_16x16x32_bf16 v[70:73], v[176:179], v[232:235], v[70:73]
	v_mfma_f32_16x16x32_bf16 v[66:69], v[184:187], v[232:235], v[66:69]
	v_mfma_f32_16x16x32_bf16 v[118:121], v[180:183], v[212:215], v[118:121]
	v_mfma_f32_16x16x32_bf16 v[114:117], v[204:207], v[212:215], v[114:117]
	v_mfma_f32_16x16x32_bf16 v[102:105], v[180:183], v[220:223], v[102:105]
	v_mfma_f32_16x16x32_bf16 v[98:101], v[204:207], v[220:223], v[98:101]
	v_mfma_f32_16x16x32_bf16 v[86:89], v[180:183], v[228:231], v[86:89]
	v_mfma_f32_16x16x32_bf16 v[82:85], v[204:207], v[228:231], v[82:85]
	v_mfma_f32_16x16x32_bf16 v[70:73], v[180:183], v[236:239], v[70:73]
	v_mfma_f32_16x16x32_bf16 v[66:69], v[204:207], v[236:239], v[66:69]
	s_setprio 0
	s_barrier
	s_add_i32 s46, s46, s4
	v_lshl_add_u64 v[240:241], s[18:19], 0, v[148:149]
	s_mov_b32 m0, s46
	ds_read_b128 v[208:211], v143 offset:16384
	ds_read_b128 v[212:215], v143 offset:17408
	ds_read_b128 v[216:219], v143 offset:18432
	ds_read_b128 v[220:223], v143 offset:19456
	ds_read_b128 v[224:227], v143 offset:20480
	ds_read_b128 v[228:231], v143 offset:21504
	ds_read_b128 v[232:235], v143 offset:22528
	ds_read_b128 v[236:239], v143 offset:23552
	global_load_lds_dwordx4 v[240:241], off
	s_add_i32 m0, s46, 0x2000
	s_add_u32 s46, s18, 0x20000
	v_lshl_add_u64 v[242:243], s[18:19], 0, v[144:145]
	s_addc_u32 s47, s19, 0
	s_add_i32 s76, s76, s4
	global_load_lds_dwordx4 v[242:243], off
	v_lshl_add_u64 v[244:245], s[46:47], 0, v[148:149]
	s_mov_b32 m0, s76
	v_lshl_add_u64 v[246:247], s[62:63], 0, v[146:147]
	global_load_lds_dwordx4 v[244:245], off
	v_lshl_add_u64 v[244:245], s[46:47], 0, v[144:145]
	s_add_i32 m0, s76, 0x2000
	s_nop 0
	global_load_lds_dwordx4 v[244:245], off
	v_lshl_add_u64 v[244:245], s[62:63], 0, v[150:151]
	s_mov_b32 m0, s5
	s_nop 0
	global_load_lds_dwordx4 v[244:245], off
	s_mov_b32 m0, s28
	s_nop 0
	global_load_lds_dwordx4 v[246:247], off
	s_waitcnt vmcnt(8)
	s_waitcnt lgkmcnt(0)
	s_barrier
; #define PG8_STAGE(bufoff, gbase, voff) do { _Pragma("unroll") for (int _i = 0; _i < 2; ++_i) \
;         __builtin_amdgcn_global_load_lds((const unsigned*)((const char*)(gbase) + (voff)[_i]), (PG8_LAS unsigned*)(lds + (bufoff) + ldsw + _i * 8192), 16, 0, 0); } while (0)
; #define PG8_LDA(dst, b, h) do { _Pragma("unroll") for (int m = 0; m < 4; ++m) _Pragma("unroll") for (int k = 0; k < 2; ++k) dst[m][k] = *(const PG8_LAS bf16x8*)(lds + PG8_SA(b, h) + aoff + m * 2048 + k * 1024); } while (0)
; #define PG8_LDB(dst, b, h) do { _Pragma("unroll") for (int n = 0; n < 2; ++n) _Pragma("unroll") for (int k = 0; k < 2; ++k) dst[n][k] = *(const PG8_LAS bf16x8*)(lds + PG8_SB(b, h) + boff + n * 2048 + k * 1024); } while (0)
; #define PG8_MMA(ai, bj, At, Bt) do { __builtin_amdgcn_s_setprio(1); _Pragma("unroll") for (int m = 0; m < 4; ++m) _Pragma("unroll") for (int n = 0; n < 2; ++n) _Pragma("unroll") for (int k = 0; k < 2; ++k) \
;         acc[ai][bj][m][n] = __builtin_amdgcn_mfma_f32_16x16x32_bf16(Bt[n][k], At[m][k], acc[ai][bj][m][n], 0, 0, 0); __builtin_amdgcn_s_setprio(0); } while (0)
; #define PG8_WAIT_V(n) asm volatile("s_waitcnt vmcnt(" #n ")" ::: "memory")
; #define PG8_WAIT_L(n) asm volatile("s_waitcnt lgkmcnt(" #n ")" ::: "memory")
; #define PG8_BAR __builtin_amdgcn_s_barrier()
; #define PG8_SCHED __builtin_amdgcn_sched_barrier(0)
; template <class Epi, class Sched, bool ALIGN_EPI = false, bool SP2 = false>
; __device__ __forceinline__ void gemm_phase(PG8_LAS unsigned char* lds, const Gemm g, const Sched& S, const Epi& E) {
;     ...
;             PG8_WAIT_V(8); PG8_WAIT_L(0); PG8_BAR; PG8_MMA(1, 0, At, B0); PG8_MMA(1, 1, At, B1); PG8_BAR; PG8_SCHED;
;             PG8_LDB(B0, 1, 0); PG8_LDB(B1, 1, 1); PG8_SCHED; PG8_LDA(At, 1, 0); PG8_STAGE(PG8_SA(0, 1), a2 + hstep, voffA);
;             PG8_WAIT_V(8); PG8_WAIT_L(0); PG8_BAR; PG8_MMA(0, 0, At, B0); PG8_MMA(0, 1, At, B1); PG8_BAR; PG8_SCHED;
	s_setprio 1
	s_waitcnt lgkmcnt(0)
	v_mfma_f32_16x16x32_bf16 v[62:65], v[160:163], v[208:211], v[62:65]
	v_mfma_f32_16x16x32_bf16 v[58:61], v[168:171], v[208:211], v[58:61]
	v_mfma_f32_16x16x32_bf16 v[46:49], v[160:163], v[216:219], v[46:49]
	v_mfma_f32_16x16x32_bf16 v[42:45], v[168:171], v[216:219], v[42:45]
	v_mfma_f32_16x16x32_bf16 v[30:33], v[160:163], v[224:227], v[30:33]
	v_mfma_f32_16x16x32_bf16 v[26:29], v[168:171], v[224:227], v[26:29]
	v_mfma_f32_16x16x32_bf16 v[14:17], v[160:163], v[232:235], v[14:17]
	v_mfma_f32_16x16x32_bf16 v[10:13], v[168:171], v[232:235], v[10:13]
	v_mfma_f32_16x16x32_bf16 v[62:65], v[164:167], v[212:215], v[62:65]
	v_mfma_f32_16x16x32_bf16 v[58:61], v[172:175], v[212:215], v[58:61]
	v_mfma_f32_16x16x32_bf16 v[46:49], v[164:167], v[220:223], v[46:49]
	v_mfma_f32_16x16x32_bf16 v[42:45], v[172:175], v[220:223], v[42:45]
	v_mfma_f32_16x16x32_bf16 v[30:33], v[164:167], v[228:231], v[30:33]
	v_mfma_f32_16x16x32_bf16 v[26:29], v[172:175], v[228:231], v[26:29]
	v_mfma_f32_16x16x32_bf16 v[14:17], v[164:167], v[236:239], v[14:17]
	v_mfma_f32_16x16x32_bf16 v[10:13], v[172:175], v[236:239], v[10:13]
	s_setprio 0
	s_setprio 1
	v_mfma_f32_16x16x32_bf16 v[54:57], v[176:179], v[208:211], v[54:57]
	v_mfma_f32_16x16x32_bf16 v[50:53], v[184:187], v[208:211], v[50:53]
	v_mfma_f32_16x16x32_bf16 v[38:41], v[176:179], v[216:219], v[38:41]
	v_mfma_f32_16x16x32_bf16 v[34:37], v[184:187], v[216:219], v[34:37]
	v_mfma_f32_16x16x32_bf16 v[22:25], v[176:179], v[224:227], v[22:25]
	v_mfma_f32_16x16x32_bf16 v[18:21], v[184:187], v[224:227], v[18:21]
	v_mfma_f32_16x16x32_bf16 v[6:9], v[176:179], v[232:235], v[6:9]
	v_mfma_f32_16x16x32_bf16 v[2:5], v[184:187], v[232:235], v[2:5]
	v_mfma_f32_16x16x32_bf16 v[54:57], v[180:183], v[212:215], v[54:57]
	v_mfma_f32_16x16x32_bf16 v[50:53], v[204:207], v[212:215], v[50:53]
	v_mfma_f32_16x16x32_bf16 v[38:41], v[180:183], v[220:223], v[38:41]
	v_mfma_f32_16x16x32_bf16 v[34:37], v[204:207], v[220:223], v[34:37]
	v_mfma_f32_16x16x32_bf16 v[22:25], v[180:183], v[228:231], v[22:25]
	v_mfma_f32_16x16x32_bf16 v[18:21], v[204:207], v[228:231], v[18:21]
	v_mfma_f32_16x16x32_bf16 v[6:9], v[180:183], v[236:239], v[6:9]
	v_mfma_f32_16x16x32_bf16 v[2:5], v[204:207], v[236:239], v[2:5]
	s_setprio 0
	s_barrier
	s_add_i32 s76, 0, 0x18000
	s_add_i32 s77, 0, 0x1c000
	v_add_u32_e32 v172, s76, v1
	v_add_u32_e32 v203, s77, v1
	ds_read_b128 v[160:163], v172
	ds_read_b128 v[164:167], v172 offset:1024
	ds_read_b128 v[168:171], v172 offset:2048
	ds_read_b128 v[172:175], v172 offset:3072
	ds_read_b128 v[176:179], v203
	ds_read_b128 v[180:183], v203 offset:1024
	ds_read_b128 v[184:187], v203 offset:2048
	ds_read_b128 v[204:207], v203 offset:3072
	s_add_u32 s46, s62, 0x20000
	s_addc_u32 s47, s63, 0
	s_mov_b32 m0, s30
	v_lshl_add_u64 v[248:249], s[46:47], 0, v[150:151]
	ds_read_b128 v[208:211], v143 offset:32768
	ds_read_b128 v[212:215], v143 offset:33792
	ds_read_b128 v[216:219], v143 offset:34816
	ds_read_b128 v[220:223], v143 offset:35840
	ds_read_b128 v[224:227], v143 offset:36864
	ds_read_b128 v[228:231], v143 offset:37888
	ds_read_b128 v[232:235], v143 offset:38912
	ds_read_b128 v[236:239], v143 offset:39936
	global_load_lds_dwordx4 v[248:249], off
	v_lshl_add_u64 v[248:249], s[46:47], 0, v[146:147]
	s_mov_b32 m0, s34
	s_nop 0
	global_load_lds_dwordx4 v[248:249], off
	s_waitcnt vmcnt(8)
	s_waitcnt lgkmcnt(0)
	s_barrier
	s_setprio 1
	s_waitcnt lgkmcnt(0)
	v_mfma_f32_16x16x32_bf16 v[126:129], v[160:163], v[208:211], v[126:129]
	v_mfma_f32_16x16x32_bf16 v[122:125], v[168:171], v[208:211], v[122:125]
	v_mfma_f32_16x16x32_bf16 v[110:113], v[160:163], v[216:219], v[110:113]
	v_mfma_f32_16x16x32_bf16 v[106:109], v[168:171], v[216:219], v[106:109]
	v_mfma_f32_16x16x32_bf16 v[94:97], v[160:163], v[224:227], v[94:97]
	v_mfma_f32_16x16x32_bf16 v[90:93], v[168:171], v[224:227], v[90:93]
	v_mfma_f32_16x16x32_bf16 v[78:81], v[160:163], v[232:235], v[78:81]
	v_mfma_f32_16x16x32_bf16 v[74:77], v[168:171], v[232:235], v[74:77]
	v_mfma_f32_16x16x32_bf16 v[126:129], v[164:167], v[212:215], v[126:129]
	v_mfma_f32_16x16x32_bf16 v[122:125], v[172:175], v[212:215], v[122:125]
	v_mfma_f32_16x16x32_bf16 v[110:113], v[164:167], v[220:223], v[110:113]
	v_mfma_f32_16x16x32_bf16 v[106:109], v[172:175], v[220:223], v[106:109]
	v_mfma_f32_16x16x32_bf16 v[94:97], v[164:167], v[228:231], v[94:97]
	v_mfma_f32_16x16x32_bf16 v[90:93], v[172:175], v[228:231], v[90:93]
	v_mfma_f32_16x16x32_bf16 v[78:81], v[164:167], v[236:239], v[78:81]
	v_mfma_f32_16x16x32_bf16 v[74:77], v[172:175], v[236:239], v[74:77]
	s_setprio 0
	s_setprio 1
	v_mfma_f32_16x16x32_bf16 v[118:121], v[176:179], v[208:211], v[118:121]
	v_mfma_f32_16x16x32_bf16 v[114:117], v[184:187], v[208:211], v[114:117]
	v_mfma_f32_16x16x32_bf16 v[102:105], v[176:179], v[216:219], v[102:105]
	v_mfma_f32_16x16x32_bf16 v[98:101], v[184:187], v[216:219], v[98:101]
	v_mfma_f32_16x16x32_bf16 v[86:89], v[176:179], v[224:227], v[86:89]
	v_mfma_f32_16x16x32_bf16 v[82:85], v[184:187], v[224:227], v[82:85]
	v_mfma_f32_16x16x32_bf16 v[70:73], v[176:179], v[232:235], v[70:73]
	v_mfma_f32_16x16x32_bf16 v[66:69], v[184:187], v[232:235], v[66:69]
	v_mfma_f32_16x16x32_bf16 v[118:121], v[180:183], v[212:215], v[118:121]
	v_mfma_f32_16x16x32_bf16 v[114:117], v[204:207], v[212:215], v[114:117]
	v_mfma_f32_16x16x32_bf16 v[102:105], v[180:183], v[220:223], v[102:105]
	v_mfma_f32_16x16x32_bf16 v[98:101], v[204:207], v[220:223], v[98:101]
	v_mfma_f32_16x16x32_bf16 v[86:89], v[180:183], v[228:231], v[86:89]
	v_mfma_f32_16x16x32_bf16 v[82:85], v[204:207], v[228:231], v[82:85]
	v_mfma_f32_16x16x32_bf16 v[70:73], v[180:183], v[236:239], v[70:73]
	v_mfma_f32_16x16x32_bf16 v[66:69], v[204:207], v[236:239], v[66:69]
	s_setprio 0
	s_barrier
; #define PG8_STAGE(bufoff, gbase, voff) do { _Pragma("unroll") for (int _i = 0; _i < 2; ++_i) \
;         __builtin_amdgcn_global_load_lds((const unsigned*)((const char*)(gbase) + (voff)[_i]), (PG8_LAS unsigned*)(lds + (bufoff) + ldsw + _i * 8192), 16, 0, 0); } while (0)
; #define PG8_LDA(dst, b, h) do { _Pragma("unroll") for (int m = 0; m < 4; ++m) _Pragma("unroll") for (int k = 0; k < 2; ++k) dst[m][k] = *(const PG8_LAS bf16x8*)(lds + PG8_SA(b, h) + aoff + m * 2048 + k * 1024); } while (0)
; #define PG8_MMA(ai, bj, At, Bt) do { __builtin_amdgcn_s_setprio(1); _Pragma("unroll") for (int m = 0; m < 4; ++m) _Pragma("unroll") for (int n = 0; n < 2; ++n) _Pragma("unroll") for (int k = 0; k < 2; ++k) \
;         acc[ai][bj][m][n] = __builtin_amdgcn_mfma_f32_16x16x32_bf16(Bt[n][k], At[m][k], acc[ai][bj][m][n], 0, 0, 0); __builtin_amdgcn_s_setprio(0); } while (0)
; #define PG8_WAIT_V(n) asm volatile("s_waitcnt vmcnt(" #n ")" ::: "memory")
; #define PG8_WAIT_L(n) asm volatile("s_waitcnt lgkmcnt(" #n ")" ::: "memory")
; #define PG8_BAR __builtin_amdgcn_s_barrier()
; #define PG8_SCHED __builtin_amdgcn_sched_barrier(0)
;     __device__ __forceinline__ void operator()(const f32x4 (&acc)[2][2][4][2], const Unit& u, int wr, int wc, int fr, int fq) const {
;         const int row0 = u.pm * BM + wr * 64 + fr, col0 = u.pn * BM + wc * 32 + 8 * fq;
;         const int tidn = (wr * 4 + wc) * 64 + fq * 16 + fr;
;         const u32x4* gp = (const u32x4*)G8 + (size_t)(u.pm * 16 + gsel + u.pn) * 8 * 512 + tidn;
;         u32x4* mp = M1 + (size_t)(u.pm * 8 + u.pn) * 16 * 512 + tidn;
;         constexpr float K255 = 1.0f / 255.0f;
; #pragma unroll
;         for (int ai = 0; ai < 2; ++ai)
; #pragma unroll
;             for (int m = 0; m < 4; ++m) { const size_t row = (size_t)(row0 + ai * HALF + m * 16);
;                 const u32x4 gw = gp[(ai * 4 + m) * 512];
; template <class Epi, class Sched, bool ALIGN_EPI = false, bool SP2 = false>
; __device__ __forceinline__ void gemm_phase(PG8_LAS unsigned char* lds, const Gemm g, const Sched& S, const Epi& E) {
;     ...
;             PG8_LDA(At, 1, 1); PG8_STAGE(PG8_SB(1, 0), b3, voffB); PG8_STAGE(PG8_SB(1, 1), b3 + hstep, voffB); PG8_STAGE(PG8_SA(1, 0), a3, voffA);
;             PG8_WAIT_V(8); PG8_WAIT_L(0); PG8_BAR; PG8_MMA(1, 0, At, B0); PG8_MMA(1, 1, At, B1); PG8_BAR; PG8_SCHED;
;     ...
;         if constexpr (ALIGN_EPI) { if (wr == 0) PG8_BAR; }
	s_add_i32 s46, s76, s4
	v_lshl_add_u64 v[240:241], v[240:241], 0, s[68:69]
	s_mov_b32 m0, s46
	ds_read_b128 v[208:211], v143 offset:49152
	ds_read_b128 v[212:215], v143 offset:50176
	ds_read_b128 v[216:219], v143 offset:51200
	ds_read_b128 v[220:223], v143 offset:52224
	ds_read_b128 v[224:227], v143 offset:53248
	ds_read_b128 v[228:231], v143 offset:54272
	ds_read_b128 v[232:235], v143 offset:55296
	ds_read_b128 v[236:239], v143 offset:56320
	global_load_lds_dwordx4 v[240:241], off
	s_add_i32 m0, s46, 0x2000
	s_add_u32 s18, s18, 0x20080
	v_lshl_add_u64 v[240:241], v[242:243], 0, s[68:69]
	s_addc_u32 s19, s19, 0
	s_add_i32 s46, s77, s4
	global_load_lds_dwordx4 v[240:241], off
	v_lshl_add_u64 v[240:241], s[18:19], 0, v[148:149]
	s_mov_b32 m0, s46
	s_nop 0
	global_load_lds_dwordx4 v[240:241], off
	v_lshl_add_u64 v[240:241], s[18:19], 0, v[144:145]
	s_add_i32 m0, s46, 0x2000
	s_nop 0
	global_load_lds_dwordx4 v[240:241], off
	v_lshl_add_u64 v[240:241], v[244:245], 0, s[68:69]
	s_mov_b32 m0, s54
	s_nop 0
	global_load_lds_dwordx4 v[240:241], off
	v_lshl_add_u64 v[240:241], v[246:247], 0, s[68:69]
	s_mov_b32 m0, s57
	s_nop 0
	global_load_lds_dwordx4 v[240:241], off
	s_waitcnt vmcnt(8)
	s_waitcnt lgkmcnt(0)
	s_barrier
	s_setprio 1
	s_waitcnt lgkmcnt(0)
	v_mfma_f32_16x16x32_bf16 v[62:65], v[160:163], v[208:211], v[62:65]
	v_mfma_f32_16x16x32_bf16 v[58:61], v[168:171], v[208:211], v[58:61]
	v_mfma_f32_16x16x32_bf16 v[46:49], v[160:163], v[216:219], v[46:49]
	v_mfma_f32_16x16x32_bf16 v[42:45], v[168:171], v[216:219], v[42:45]
	v_mfma_f32_16x16x32_bf16 v[30:33], v[160:163], v[224:227], v[30:33]
	v_mfma_f32_16x16x32_bf16 v[26:29], v[168:171], v[224:227], v[26:29]
	v_mfma_f32_16x16x32_bf16 v[14:17], v[160:163], v[232:235], v[14:17]
	v_mfma_f32_16x16x32_bf16 v[10:13], v[168:171], v[232:235], v[10:13]
	v_mfma_f32_16x16x32_bf16 v[62:65], v[164:167], v[212:215], v[62:65]
	v_mfma_f32_16x16x32_bf16 v[58:61], v[172:175], v[212:215], v[58:61]
	v_mfma_f32_16x16x32_bf16 v[46:49], v[164:167], v[220:223], v[46:49]
	v_mfma_f32_16x16x32_bf16 v[42:45], v[172:175], v[220:223], v[42:45]
	v_mfma_f32_16x16x32_bf16 v[30:33], v[164:167], v[228:231], v[30:33]
	v_mfma_f32_16x16x32_bf16 v[26:29], v[172:175], v[228:231], v[26:29]
	v_mfma_f32_16x16x32_bf16 v[14:17], v[164:167], v[236:239], v[14:17]
	v_mfma_f32_16x16x32_bf16 v[10:13], v[172:175], v[236:239], v[10:13]
	s_setprio 0
	s_setprio 1
	v_mfma_f32_16x16x32_bf16 v[54:57], v[176:179], v[208:211], v[54:57]
	v_mfma_f32_16x16x32_bf16 v[50:53], v[184:187], v[208:211], v[50:53]
	v_mfma_f32_16x16x32_bf16 v[38:41], v[176:179], v[216:219], v[38:41]
	v_mfma_f32_16x16x32_bf16 v[34:37], v[184:187], v[216:219], v[34:37]
	v_mfma_f32_16x16x32_bf16 v[22:25], v[176:179], v[224:227], v[22:25]
	v_mfma_f32_16x16x32_bf16 v[18:21], v[184:187], v[224:227], v[18:21]
	v_mfma_f32_16x16x32_bf16 v[6:9], v[176:179], v[232:235], v[6:9]
	v_mfma_f32_16x16x32_bf16 v[2:5], v[184:187], v[232:235], v[2:5]
	v_mfma_f32_16x16x32_bf16 v[54:57], v[180:183], v[212:215], v[54:57]
	v_mfma_f32_16x16x32_bf16 v[50:53], v[204:207], v[212:215], v[50:53]
	v_mfma_f32_16x16x32_bf16 v[38:41], v[180:183], v[220:223], v[38:41]
	v_mfma_f32_16x16x32_bf16 v[34:37], v[204:207], v[220:223], v[34:37]
	v_mfma_f32_16x16x32_bf16 v[22:25], v[180:183], v[228:231], v[22:25]
	v_mfma_f32_16x16x32_bf16 v[18:21], v[204:207], v[228:231], v[18:21]
	v_mfma_f32_16x16x32_bf16 v[6:9], v[180:183], v[236:239], v[6:9]
	v_mfma_f32_16x16x32_bf16 v[2:5], v[204:207], v[236:239], v[2:5]
	s_setprio 0
	s_barrier
	s_add_i32 s79, s79, 2
	s_add_u32 s58, s58, 0x100
	s_addc_u32 s59, s59, 0
	s_add_u32 s85, s85, 0x100
	s_addc_u32 s78, s78, 0
	s_cmp_gt_u32 s79, 5
	s_cbranch_scc0 .LBB0_136
	s_lshl_b32 s11, s67, 4
	s_add_i32 s18, s11, s86
	s_ashr_i32 s19, s18, 31
	s_lshl_b64 s[46:47], s[18:19], 16
	v_lshl_add_u64 v[162:163], v[152:153], 0, s[46:47]
	s_lshl_b32 s11, s67, 3
	s_sub_i32 s18, s18, s11
	s_ashr_i32 s19, s18, 31
	s_lshl_b64 s[18:19], s[18:19], 17
	v_lshl_add_u64 v[160:161], v[154:155], 0, s[18:19]
	s_mov_b32 s47, 0
	global_load_dwordx4 v[168:171], v[162:163], off
	s_mov_b32 s46, 0x2000
	v_lshl_add_u64 v[164:165], v[162:163], 0, s[46:47]
	global_load_dwordx4 v[172:175], v[164:165], off
	s_mov_b32 s46, 0x4000
	v_lshl_add_u64 v[164:165], v[162:163], 0, s[46:47]
	global_load_dwordx4 v[176:179], v[164:165], off
	s_mov_b32 s46, 0x6000
	v_lshl_add_u64 v[164:165], v[162:163], 0, s[46:47]
	global_load_dwordx4 v[180:183], v[164:165], off
	s_mov_b32 s46, 0x8000
	v_lshl_add_u64 v[164:165], v[162:163], 0, s[46:47]
	global_load_dwordx4 v[184:187], v[164:165], off
	s_mov_b32 s46, 0xa000
	v_lshl_add_u64 v[164:165], v[162:163], 0, s[46:47]
	global_load_dwordx4 v[204:207], v[164:165], off
	s_mov_b32 s46, 0xc000
	v_lshl_add_u64 v[164:165], v[162:163], 0, s[46:47]
	global_load_dwordx4 v[208:211], v[164:165], off
	s_mov_b32 s46, 0xe000
	v_lshl_add_u64 v[164:165], v[162:163], 0, s[46:47]
	global_load_dwordx4 v[212:215], v[164:165], off
	s_and_b64 vcc, exec, s[8:9]
	s_cbranch_vccz .Lg0_nobar
	s_barrier
; __device__ __forceinline__ unsigned cvt_pk_bf16(float lo, float hi) { const f32x2c_t v = {lo, hi}; const bf16x2c_t b = __builtin_convertvector(v, bf16x2c_t); return __builtin_bit_cast(unsigned, b); }
; __device__ __forceinline__ float bf_lo(unsigned w) { return __uint_as_float(w << 16); }
; __device__ __forceinline__ float bf_hi(unsigned w) { return __uint_as_float(w & 0xffff0000u); }
;     __device__ __forceinline__ void operator()(const f32x4 (&acc)[2][2][4][2], const Unit& u, int wr, int wc, int fr, int fq) const {
;     ...
;                 const u32x4 gw = gp[(ai * 4 + m) * 512];
;                 u32x4 pw[2];
;                 if (SECOND) { pw[0] = mp[((ai * 4 + m) * 2 + 0) * 512]; pw[1] = mp[((ai * 4 + m) * 2 + 1) * 512]; }
; #pragma unroll
;                 for (int bj = 0; bj < 2; ++bj) { const unsigned gx = bj ? gw.z : gw.x, gy = bj ? gw.w : gw.y;
;                     const f32x4 g0 = (f32x4){(float)(gx & 255u), (float)((gx >> 8) & 255u), (float)((gx >> 16) & 255u), (float)(gx >> 24)} * K255,
;                                 g1 = (f32x4){(float)(gy & 255u), (float)((gy >> 8) & 255u), (float)((gy >> 16) & 255u), (float)(gy >> 24)} * K255;
;                     f32x4 v0 = acc[ai][bj][m][0] * g0, v1 = acc[ai][bj][m][1] * g1;
;                     if (SECOND) { const u32x4 p = pw[bj];
;                         v0 = v0 + (f32x4){bf_lo(p.x), bf_hi(p.x), bf_lo(p.y), bf_hi(p.y)}; v1 = v1 + (f32x4){bf_lo(p.z), bf_hi(p.z), bf_lo(p.w), bf_hi(p.w)}; }
;                     u32x4 w; w.x = cvt_pk_bf16(v0[0], v0[1]); w.y = cvt_pk_bf16(v0[2], v0[3]); w.z = cvt_pk_bf16(v1[0], v1[1]); w.w = cvt_pk_bf16(v1[2], v1[3]);
;                     if (SECOND) *(u32x4*)(MG + row * DM + col0 + bj * HALF) = w; else mp[((ai * 4 + m) * 2 + bj) * 512] = w; }
.Lg0_nobar:
	s_waitcnt vmcnt(7)
	v_cvt_f32_ubyte0_e32 v216, v168
	v_cvt_f32_ubyte1_e32 v217, v168
	v_cvt_f32_ubyte2_e32 v218, v168
	v_cvt_f32_ubyte3_e32 v219, v168
	v_cvt_f32_ubyte0_e32 v220, v169
	v_cvt_f32_ubyte1_e32 v221, v169
	v_cvt_f32_ubyte2_e32 v222, v169
	v_cvt_f32_ubyte3_e32 v223, v169
	v_pk_mul_f32 v[216:217], v[216:217], s[26:27] op_sel_hi:[1,0]
	v_pk_mul_f32 v[218:219], v[218:219], s[26:27] op_sel_hi:[1,0]
	v_pk_mul_f32 v[220:221], v[220:221], s[26:27] op_sel_hi:[1,0]
	v_pk_mul_f32 v[222:223], v[222:223], s[26:27] op_sel_hi:[1,0]
	v_pk_mul_f32 v[126:127], v[126:127], v[216:217]
	v_pk_mul_f32 v[128:129], v[128:129], v[218:219]
	v_pk_mul_f32 v[122:123], v[122:123], v[220:221]
	v_pk_mul_f32 v[124:125], v[124:125], v[222:223]
	v_cvt_pk_bf16_f32 v224, v126, v127
	v_cvt_pk_bf16_f32 v225, v128, v129
	v_cvt_pk_bf16_f32 v226, v122, v123
	v_cvt_pk_bf16_f32 v227, v124, v125
	global_store_dwordx4 v[160:161], v[224:227], off
	v_cvt_f32_ubyte0_e32 v216, v170
	v_cvt_f32_ubyte1_e32 v217, v170
	v_cvt_f32_ubyte2_e32 v218, v170
	v_cvt_f32_ubyte3_e32 v219, v170
	v_cvt_f32_ubyte0_e32 v220, v171
	v_cvt_f32_ubyte1_e32 v221, v171
	v_cvt_f32_ubyte2_e32 v222, v171
	v_cvt_f32_ubyte3_e32 v223, v171
	v_pk_mul_f32 v[216:217], v[216:217], s[26:27] op_sel_hi:[1,0]
	v_pk_mul_f32 v[218:219], v[218:219], s[26:27] op_sel_hi:[1,0]
	v_pk_mul_f32 v[220:221], v[220:221], s[26:27] op_sel_hi:[1,0]
	v_pk_mul_f32 v[222:223], v[222:223], s[26:27] op_sel_hi:[1,0]
	v_pk_mul_f32 v[118:119], v[118:119], v[216:217]
	v_pk_mul_f32 v[120:121], v[120:121], v[218:219]
	v_pk_mul_f32 v[114:115], v[114:115], v[220:221]
	v_pk_mul_f32 v[116:117], v[116:117], v[222:223]
	v_cvt_pk_bf16_f32 v228, v118, v119
	v_cvt_pk_bf16_f32 v229, v120, v121
	v_cvt_pk_bf16_f32 v230, v114, v115
	v_cvt_pk_bf16_f32 v231, v116, v117
	s_mov_b32 s46, 0x2000
	v_lshl_add_u64 v[166:167], v[160:161], 0, s[46:47]
	global_store_dwordx4 v[166:167], v[228:231], off
	s_waitcnt vmcnt(8)
	v_cvt_f32_ubyte0_e32 v216, v172
	v_cvt_f32_ubyte1_e32 v217, v172
	v_cvt_f32_ubyte2_e32 v218, v172
	v_cvt_f32_ubyte3_e32 v219, v172
	v_cvt_f32_ubyte0_e32 v220, v173
	v_cvt_f32_ubyte1_e32 v221, v173
	v_cvt_f32_ubyte2_e32 v222, v173
	v_cvt_f32_ubyte3_e32 v223, v173
	v_pk_mul_f32 v[216:217], v[216:217], s[26:27] op_sel_hi:[1,0]
	v_pk_mul_f32 v[218:219], v[218:219], s[26:27] op_sel_hi:[1,0]
	v_pk_mul_f32 v[220:221], v[220:221], s[26:27] op_sel_hi:[1,0]
	v_pk_mul_f32 v[222:223], v[222:223], s[26:27] op_sel_hi:[1,0]
	v_pk_mul_f32 v[110:111], v[110:111], v[216:217]
	v_pk_mul_f32 v[112:113], v[112:113], v[218:219]
	v_pk_mul_f32 v[106:107], v[106:107], v[220:221]
	v_pk_mul_f32 v[108:109], v[108:109], v[222:223]
	v_cvt_pk_bf16_f32 v224, v110, v111
	v_cvt_pk_bf16_f32 v225, v112, v113
	v_cvt_pk_bf16_f32 v226, v106, v107
	v_cvt_pk_bf16_f32 v227, v108, v109
	s_mov_b32 s46, 0x4000
	v_lshl_add_u64 v[166:167], v[160:161], 0, s[46:47]
	global_store_dwordx4 v[166:167], v[224:227], off
	v_cvt_f32_ubyte0_e32 v216, v174
	v_cvt_f32_ubyte1_e32 v217, v174
	v_cvt_f32_ubyte2_e32 v218, v174
	v_cvt_f32_ubyte3_e32 v219, v174
	v_cvt_f32_ubyte0_e32 v220, v175
	v_cvt_f32_ubyte1_e32 v221, v175
	v_cvt_f32_ubyte2_e32 v222, v175
	v_cvt_f32_ubyte3_e32 v223, v175
	v_pk_mul_f32 v[216:217], v[216:217], s[26:27] op_sel_hi:[1,0]
	v_pk_mul_f32 v[218:219], v[218:219], s[26:27] op_sel_hi:[1,0]
	v_pk_mul_f32 v[220:221], v[220:221], s[26:27] op_sel_hi:[1,0]
	v_pk_mul_f32 v[222:223], v[222:223], s[26:27] op_sel_hi:[1,0]
	v_pk_mul_f32 v[102:103], v[102:103], v[216:217]
	v_pk_mul_f32 v[104:105], v[104:105], v[218:219]
	v_pk_mul_f32 v[98:99], v[98:99], v[220:221]
	v_pk_mul_f32 v[100:101], v[100:101], v[222:223]
	v_cvt_pk_bf16_f32 v228, v102, v103
	v_cvt_pk_bf16_f32 v229, v104, v105
	v_cvt_pk_bf16_f32 v230, v98, v99
	v_cvt_pk_bf16_f32 v231, v100, v101
	s_mov_b32 s46, 0x6000
	v_lshl_add_u64 v[166:167], v[160:161], 0, s[46:47]
	global_store_dwordx4 v[166:167], v[228:231], off
	s_waitcnt vmcnt(9)
	v_cvt_f32_ubyte0_e32 v216, v176
	v_cvt_f32_ubyte1_e32 v217, v176
	v_cvt_f32_ubyte2_e32 v218, v176
	v_cvt_f32_ubyte3_e32 v219, v176
	v_cvt_f32_ubyte0_e32 v220, v177
	v_cvt_f32_ubyte1_e32 v221, v177
	v_cvt_f32_ubyte2_e32 v222, v177
	v_cvt_f32_ubyte3_e32 v223, v177
	v_pk_mul_f32 v[216:217], v[216:217], s[26:27] op_sel_hi:[1,0]
	v_pk_mul_f32 v[218:219], v[218:219], s[26:27] op_sel_hi:[1,0]
	v_pk_mul_f32 v[220:221], v[220:221], s[26:27] op_sel_hi:[1,0]
	v_pk_mul_f32 v[222:223], v[222:223], s[26:27] op_sel_hi:[1,0]
	v_pk_mul_f32 v[94:95], v[94:95], v[216:217]
	v_pk_mul_f32 v[96:97], v[96:97], v[218:219]
	v_pk_mul_f32 v[90:91], v[90:91], v[220:221]
	v_pk_mul_f32 v[92:93], v[92:93], v[222:223]
	v_cvt_pk_bf16_f32 v224, v94, v95
	v_cvt_pk_bf16_f32 v225, v96, v97
	v_cvt_pk_bf16_f32 v226, v90, v91
	v_cvt_pk_bf16_f32 v227, v92, v93
	s_mov_b32 s46, 0x8000
	v_lshl_add_u64 v[166:167], v[160:161], 0, s[46:47]
	global_store_dwordx4 v[166:167], v[224:227], off
	v_cvt_f32_ubyte0_e32 v216, v178
	v_cvt_f32_ubyte1_e32 v217, v178
	v_cvt_f32_ubyte2_e32 v218, v178
	v_cvt_f32_ubyte3_e32 v219, v178
	v_cvt_f32_ubyte0_e32 v220, v179
	v_cvt_f32_ubyte1_e32 v221, v179
	v_cvt_f32_ubyte2_e32 v222, v179
	v_cvt_f32_ubyte3_e32 v223, v179
	v_pk_mul_f32 v[216:217], v[216:217], s[26:27] op_sel_hi:[1,0]
	v_pk_mul_f32 v[218:219], v[218:219], s[26:27] op_sel_hi:[1,0]
	v_pk_mul_f32 v[220:221], v[220:221], s[26:27] op_sel_hi:[1,0]
	v_pk_mul_f32 v[222:223], v[222:223], s[26:27] op_sel_hi:[1,0]
	v_pk_mul_f32 v[86:87], v[86:87], v[216:217]
	v_pk_mul_f32 v[88:89], v[88:89], v[218:219]
	v_pk_mul_f32 v[82:83], v[82:83], v[220:221]
	v_pk_mul_f32 v[84:85], v[84:85], v[222:223]
	v_cvt_pk_bf16_f32 v228, v86, v87
	v_cvt_pk_bf16_f32 v229, v88, v89
	v_cvt_pk_bf16_f32 v230, v82, v83
	v_cvt_pk_bf16_f32 v231, v84, v85
	s_mov_b32 s46, 0xa000
	v_lshl_add_u64 v[166:167], v[160:161], 0, s[46:47]
	global_store_dwordx4 v[166:167], v[228:231], off
	s_waitcnt vmcnt(10)
; __device__ __forceinline__ unsigned cvt_pk_bf16(float lo, float hi) { const f32x2c_t v = {lo, hi}; const bf16x2c_t b = __builtin_convertvector(v, bf16x2c_t); return __builtin_bit_cast(unsigned, b); }
; __device__ __forceinline__ float bf_lo(unsigned w) { return __uint_as_float(w << 16); }
; __device__ __forceinline__ float bf_hi(unsigned w) { return __uint_as_float(w & 0xffff0000u); }
;     __device__ __forceinline__ void operator()(const f32x4 (&acc)[2][2][4][2], const Unit& u, int wr, int wc, int fr, int fq) const {
;     ...
;                 for (int bj = 0; bj < 2; ++bj) { const unsigned gx = bj ? gw.z : gw.x, gy = bj ? gw.w : gw.y;
;                     const f32x4 g0 = (f32x4){(float)(gx & 255u), (float)((gx >> 8) & 255u), (float)((gx >> 16) & 255u), (float)(gx >> 24)} * K255,
;                                 g1 = (f32x4){(float)(gy & 255u), (float)((gy >> 8) & 255u), (float)((gy >> 16) & 255u), (float)(gy >> 24)} * K255;
;                     f32x4 v0 = acc[ai][bj][m][0] * g0, v1 = acc[ai][bj][m][1] * g1;
;                     if (SECOND) { const u32x4 p = pw[bj];
;                         v0 = v0 + (f32x4){bf_lo(p.x), bf_hi(p.x), bf_lo(p.y), bf_hi(p.y)}; v1 = v1 + (f32x4){bf_lo(p.z), bf_hi(p.z), bf_lo(p.w), bf_hi(p.w)}; }
;                     u32x4 w; w.x = cvt_pk_bf16(v0[0], v0[1]); w.y = cvt_pk_bf16(v0[2], v0[3]); w.z = cvt_pk_bf16(v1[0], v1[1]); w.w = cvt_pk_bf16(v1[2], v1[3]);
;                     if (SECOND) *(u32x4*)(MG + row * DM + col0 + bj * HALF) = w; else mp[((ai * 4 + m) * 2 + bj) * 512] = w; }
	v_cvt_f32_ubyte0_e32 v216, v180
	v_cvt_f32_ubyte1_e32 v217, v180
	v_cvt_f32_ubyte2_e32 v218, v180
	v_cvt_f32_ubyte3_e32 v219, v180
	v_cvt_f32_ubyte0_e32 v220, v181
	v_cvt_f32_ubyte1_e32 v221, v181
	v_cvt_f32_ubyte2_e32 v222, v181
	v_cvt_f32_ubyte3_e32 v223, v181
	v_pk_mul_f32 v[216:217], v[216:217], s[26:27] op_sel_hi:[1,0]
	v_pk_mul_f32 v[218:219], v[218:219], s[26:27] op_sel_hi:[1,0]
	v_pk_mul_f32 v[220:221], v[220:221], s[26:27] op_sel_hi:[1,0]
	v_pk_mul_f32 v[222:223], v[222:223], s[26:27] op_sel_hi:[1,0]
	v_pk_mul_f32 v[78:79], v[78:79], v[216:217]
	v_pk_mul_f32 v[80:81], v[80:81], v[218:219]
	v_pk_mul_f32 v[74:75], v[74:75], v[220:221]
	v_pk_mul_f32 v[76:77], v[76:77], v[222:223]
	v_cvt_pk_bf16_f32 v224, v78, v79
	v_cvt_pk_bf16_f32 v225, v80, v81
	v_cvt_pk_bf16_f32 v226, v74, v75
	v_cvt_pk_bf16_f32 v227, v76, v77
	s_mov_b32 s46, 0xc000
	v_lshl_add_u64 v[166:167], v[160:161], 0, s[46:47]
	global_store_dwordx4 v[166:167], v[224:227], off
	v_cvt_f32_ubyte0_e32 v216, v182
	v_cvt_f32_ubyte1_e32 v217, v182
	v_cvt_f32_ubyte2_e32 v218, v182
	v_cvt_f32_ubyte3_e32 v219, v182
	v_cvt_f32_ubyte0_e32 v220, v183
	v_cvt_f32_ubyte1_e32 v221, v183
	v_cvt_f32_ubyte2_e32 v222, v183
	v_cvt_f32_ubyte3_e32 v223, v183
	v_pk_mul_f32 v[216:217], v[216:217], s[26:27] op_sel_hi:[1,0]
	v_pk_mul_f32 v[218:219], v[218:219], s[26:27] op_sel_hi:[1,0]
	v_pk_mul_f32 v[220:221], v[220:221], s[26:27] op_sel_hi:[1,0]
	v_pk_mul_f32 v[222:223], v[222:223], s[26:27] op_sel_hi:[1,0]
	v_pk_mul_f32 v[70:71], v[70:71], v[216:217]
	v_pk_mul_f32 v[72:73], v[72:73], v[218:219]
	v_pk_mul_f32 v[66:67], v[66:67], v[220:221]
	v_pk_mul_f32 v[68:69], v[68:69], v[222:223]
	v_cvt_pk_bf16_f32 v228, v70, v71
	v_cvt_pk_bf16_f32 v229, v72, v73
	v_cvt_pk_bf16_f32 v230, v66, v67
	v_cvt_pk_bf16_f32 v231, v68, v69
	s_mov_b32 s46, 0xe000
	v_lshl_add_u64 v[166:167], v[160:161], 0, s[46:47]
	global_store_dwordx4 v[166:167], v[228:231], off
	s_waitcnt vmcnt(11)
	v_cvt_f32_ubyte0_e32 v216, v184
	v_cvt_f32_ubyte1_e32 v217, v184
	v_cvt_f32_ubyte2_e32 v218, v184
	v_cvt_f32_ubyte3_e32 v219, v184
	v_cvt_f32_ubyte0_e32 v220, v185
	v_cvt_f32_ubyte1_e32 v221, v185
	v_cvt_f32_ubyte2_e32 v222, v185
	v_cvt_f32_ubyte3_e32 v223, v185
	v_pk_mul_f32 v[216:217], v[216:217], s[26:27] op_sel_hi:[1,0]
	v_pk_mul_f32 v[218:219], v[218:219], s[26:27] op_sel_hi:[1,0]
	v_pk_mul_f32 v[220:221], v[220:221], s[26:27] op_sel_hi:[1,0]
	v_pk_mul_f32 v[222:223], v[222:223], s[26:27] op_sel_hi:[1,0]
	v_pk_mul_f32 v[62:63], v[62:63], v[216:217]
	v_pk_mul_f32 v[64:65], v[64:65], v[218:219]
	v_pk_mul_f32 v[58:59], v[58:59], v[220:221]
	v_pk_mul_f32 v[60:61], v[60:61], v[222:223]
	v_cvt_pk_bf16_f32 v224, v62, v63
	v_cvt_pk_bf16_f32 v225, v64, v65
	v_cvt_pk_bf16_f32 v226, v58, v59
	v_cvt_pk_bf16_f32 v227, v60, v61
	s_mov_b32 s46, 0x10000
	v_lshl_add_u64 v[166:167], v[160:161], 0, s[46:47]
	global_store_dwordx4 v[166:167], v[224:227], off
	v_cvt_f32_ubyte0_e32 v216, v186
	v_cvt_f32_ubyte1_e32 v217, v186
	v_cvt_f32_ubyte2_e32 v218, v186
	v_cvt_f32_ubyte3_e32 v219, v186
	v_cvt_f32_ubyte0_e32 v220, v187
	v_cvt_f32_ubyte1_e32 v221, v187
	v_cvt_f32_ubyte2_e32 v222, v187
	v_cvt_f32_ubyte3_e32 v223, v187
	v_pk_mul_f32 v[216:217], v[216:217], s[26:27] op_sel_hi:[1,0]
	v_pk_mul_f32 v[218:219], v[218:219], s[26:27] op_sel_hi:[1,0]
	v_pk_mul_f32 v[220:221], v[220:221], s[26:27] op_sel_hi:[1,0]
	v_pk_mul_f32 v[222:223], v[222:223], s[26:27] op_sel_hi:[1,0]
	v_pk_mul_f32 v[54:55], v[54:55], v[216:217]
	v_pk_mul_f32 v[56:57], v[56:57], v[218:219]
	v_pk_mul_f32 v[50:51], v[50:51], v[220:221]
	v_pk_mul_f32 v[52:53], v[52:53], v[222:223]
	v_cvt_pk_bf16_f32 v228, v54, v55
	v_cvt_pk_bf16_f32 v229, v56, v57
	v_cvt_pk_bf16_f32 v230, v50, v51
	v_cvt_pk_bf16_f32 v231, v52, v53
	s_mov_b32 s46, 0x12000
	v_lshl_add_u64 v[166:167], v[160:161], 0, s[46:47]
	global_store_dwordx4 v[166:167], v[228:231], off
	s_waitcnt vmcnt(12)
	v_cvt_f32_ubyte0_e32 v216, v204
	v_cvt_f32_ubyte1_e32 v217, v204
	v_cvt_f32_ubyte2_e32 v218, v204
	v_cvt_f32_ubyte3_e32 v219, v204
	v_cvt_f32_ubyte0_e32 v220, v205
	v_cvt_f32_ubyte1_e32 v221, v205
	v_cvt_f32_ubyte2_e32 v222, v205
	v_cvt_f32_ubyte3_e32 v223, v205
	v_pk_mul_f32 v[216:217], v[216:217], s[26:27] op_sel_hi:[1,0]
	v_pk_mul_f32 v[218:219], v[218:219], s[26:27] op_sel_hi:[1,0]
	v_pk_mul_f32 v[220:221], v[220:221], s[26:27] op_sel_hi:[1,0]
	v_pk_mul_f32 v[222:223], v[222:223], s[26:27] op_sel_hi:[1,0]
	v_pk_mul_f32 v[46:47], v[46:47], v[216:217]
	v_pk_mul_f32 v[48:49], v[48:49], v[218:219]
	v_pk_mul_f32 v[42:43], v[42:43], v[220:221]
	v_pk_mul_f32 v[44:45], v[44:45], v[222:223]
	v_cvt_pk_bf16_f32 v224, v46, v47
	v_cvt_pk_bf16_f32 v225, v48, v49
	v_cvt_pk_bf16_f32 v226, v42, v43
	v_cvt_pk_bf16_f32 v227, v44, v45
	s_mov_b32 s46, 0x14000
	v_lshl_add_u64 v[166:167], v[160:161], 0, s[46:47]
	global_store_dwordx4 v[166:167], v[224:227], off
	v_cvt_f32_ubyte0_e32 v216, v206
	v_cvt_f32_ubyte1_e32 v217, v206
	v_cvt_f32_ubyte2_e32 v218, v206
	v_cvt_f32_ubyte3_e32 v219, v206
	v_cvt_f32_ubyte0_e32 v220, v207
	v_cvt_f32_ubyte1_e32 v221, v207
	v_cvt_f32_ubyte2_e32 v222, v207
	v_cvt_f32_ubyte3_e32 v223, v207
	v_pk_mul_f32 v[216:217], v[216:217], s[26:27] op_sel_hi:[1,0]
	v_pk_mul_f32 v[218:219], v[218:219], s[26:27] op_sel_hi:[1,0]
	v_pk_mul_f32 v[220:221], v[220:221], s[26:27] op_sel_hi:[1,0]
	v_pk_mul_f32 v[222:223], v[222:223], s[26:27] op_sel_hi:[1,0]
	v_pk_mul_f32 v[38:39], v[38:39], v[216:217]
	v_pk_mul_f32 v[40:41], v[40:41], v[218:219]
	v_pk_mul_f32 v[34:35], v[34:35], v[220:221]
	v_pk_mul_f32 v[36:37], v[36:37], v[222:223]
	v_cvt_pk_bf16_f32 v228, v38, v39
	v_cvt_pk_bf16_f32 v229, v40, v41
	v_cvt_pk_bf16_f32 v230, v34, v35
	v_cvt_pk_bf16_f32 v231, v36, v37
	s_mov_b32 s46, 0x16000
	v_lshl_add_u64 v[166:167], v[160:161], 0, s[46:47]
	global_store_dwordx4 v[166:167], v[228:231], off
	s_waitcnt vmcnt(13)
; __device__ __forceinline__ unsigned cvt_pk_bf16(float lo, float hi) { const f32x2c_t v = {lo, hi}; const bf16x2c_t b = __builtin_convertvector(v, bf16x2c_t); return __builtin_bit_cast(unsigned, b); }
; __device__ __forceinline__ float bf_lo(unsigned w) { return __uint_as_float(w << 16); }
; __device__ __forceinline__ float bf_hi(unsigned w) { return __uint_as_float(w & 0xffff0000u); }
;     __device__ __forceinline__ void operator()(const f32x4 (&acc)[2][2][4][2], const Unit& u, int wr, int wc, int fr, int fq) const {
;     ...
;                 for (int bj = 0; bj < 2; ++bj) { const unsigned gx = bj ? gw.z : gw.x, gy = bj ? gw.w : gw.y;
;                     const f32x4 g0 = (f32x4){(float)(gx & 255u), (float)((gx >> 8) & 255u), (float)((gx >> 16) & 255u), (float)(gx >> 24)} * K255,
;                                 g1 = (f32x4){(float)(gy & 255u), (float)((gy >> 8) & 255u), (float)((gy >> 16) & 255u), (float)(gy >> 24)} * K255;
;                     f32x4 v0 = acc[ai][bj][m][0] * g0, v1 = acc[ai][bj][m][1] * g1;
;                     if (SECOND) { const u32x4 p = pw[bj];
;                         v0 = v0 + (f32x4){bf_lo(p.x), bf_hi(p.x), bf_lo(p.y), bf_hi(p.y)}; v1 = v1 + (f32x4){bf_lo(p.z), bf_hi(p.z), bf_lo(p.w), bf_hi(p.w)}; }
;                     u32x4 w; w.x = cvt_pk_bf16(v0[0], v0[1]); w.y = cvt_pk_bf16(v0[2], v0[3]); w.z = cvt_pk_bf16(v1[0], v1[1]); w.w = cvt_pk_bf16(v1[2], v1[3]);
;                     if (SECOND) *(u32x4*)(MG + row * DM + col0 + bj * HALF) = w; else mp[((ai * 4 + m) * 2 + bj) * 512] = w; }
;                 if (m == 3) asm volatile("" ::: "memory"); }
	v_cvt_f32_ubyte0_e32 v216, v208
	v_cvt_f32_ubyte1_e32 v217, v208
	v_cvt_f32_ubyte2_e32 v218, v208
	v_cvt_f32_ubyte3_e32 v219, v208
	v_cvt_f32_ubyte0_e32 v220, v209
	v_cvt_f32_ubyte1_e32 v221, v209
	v_cvt_f32_ubyte2_e32 v222, v209
	v_cvt_f32_ubyte3_e32 v223, v209
	v_pk_mul_f32 v[216:217], v[216:217], s[26:27] op_sel_hi:[1,0]
	v_pk_mul_f32 v[218:219], v[218:219], s[26:27] op_sel_hi:[1,0]
	v_pk_mul_f32 v[220:221], v[220:221], s[26:27] op_sel_hi:[1,0]
	v_pk_mul_f32 v[222:223], v[222:223], s[26:27] op_sel_hi:[1,0]
	v_pk_mul_f32 v[30:31], v[30:31], v[216:217]
	v_pk_mul_f32 v[32:33], v[32:33], v[218:219]
	v_pk_mul_f32 v[26:27], v[26:27], v[220:221]
	v_pk_mul_f32 v[28:29], v[28:29], v[222:223]
	v_cvt_pk_bf16_f32 v224, v30, v31
	v_cvt_pk_bf16_f32 v225, v32, v33
	v_cvt_pk_bf16_f32 v226, v26, v27
	v_cvt_pk_bf16_f32 v227, v28, v29
	s_mov_b32 s46, 0x18000
	v_lshl_add_u64 v[166:167], v[160:161], 0, s[46:47]
	global_store_dwordx4 v[166:167], v[224:227], off
	v_cvt_f32_ubyte0_e32 v216, v210
	v_cvt_f32_ubyte1_e32 v217, v210
	v_cvt_f32_ubyte2_e32 v218, v210
	v_cvt_f32_ubyte3_e32 v219, v210
	v_cvt_f32_ubyte0_e32 v220, v211
	v_cvt_f32_ubyte1_e32 v221, v211
	v_cvt_f32_ubyte2_e32 v222, v211
	v_cvt_f32_ubyte3_e32 v223, v211
	v_pk_mul_f32 v[216:217], v[216:217], s[26:27] op_sel_hi:[1,0]
	v_pk_mul_f32 v[218:219], v[218:219], s[26:27] op_sel_hi:[1,0]
	v_pk_mul_f32 v[220:221], v[220:221], s[26:27] op_sel_hi:[1,0]
	v_pk_mul_f32 v[222:223], v[222:223], s[26:27] op_sel_hi:[1,0]
	v_pk_mul_f32 v[22:23], v[22:23], v[216:217]
	v_pk_mul_f32 v[24:25], v[24:25], v[218:219]
	v_pk_mul_f32 v[18:19], v[18:19], v[220:221]
	v_pk_mul_f32 v[20:21], v[20:21], v[222:223]
	v_cvt_pk_bf16_f32 v228, v22, v23
	v_cvt_pk_bf16_f32 v229, v24, v25
	v_cvt_pk_bf16_f32 v230, v18, v19
	v_cvt_pk_bf16_f32 v231, v20, v21
	s_mov_b32 s46, 0x1a000
	v_lshl_add_u64 v[166:167], v[160:161], 0, s[46:47]
	global_store_dwordx4 v[166:167], v[228:231], off
	s_waitcnt vmcnt(14)
	v_cvt_f32_ubyte0_e32 v216, v212
	v_cvt_f32_ubyte1_e32 v217, v212
	v_cvt_f32_ubyte2_e32 v218, v212
	v_cvt_f32_ubyte3_e32 v219, v212
	v_cvt_f32_ubyte0_e32 v220, v213
	v_cvt_f32_ubyte1_e32 v221, v213
	v_cvt_f32_ubyte2_e32 v222, v213
	v_cvt_f32_ubyte3_e32 v223, v213
	v_pk_mul_f32 v[216:217], v[216:217], s[26:27] op_sel_hi:[1,0]
	v_pk_mul_f32 v[218:219], v[218:219], s[26:27] op_sel_hi:[1,0]
	v_pk_mul_f32 v[220:221], v[220:221], s[26:27] op_sel_hi:[1,0]
	v_pk_mul_f32 v[222:223], v[222:223], s[26:27] op_sel_hi:[1,0]
	v_pk_mul_f32 v[14:15], v[14:15], v[216:217]
	v_pk_mul_f32 v[16:17], v[16:17], v[218:219]
	v_pk_mul_f32 v[10:11], v[10:11], v[220:221]
	v_pk_mul_f32 v[12:13], v[12:13], v[222:223]
	v_cvt_pk_bf16_f32 v224, v14, v15
	v_cvt_pk_bf16_f32 v225, v16, v17
	v_cvt_pk_bf16_f32 v226, v10, v11
	v_cvt_pk_bf16_f32 v227, v12, v13
	s_mov_b32 s46, 0x1c000
	v_lshl_add_u64 v[166:167], v[160:161], 0, s[46:47]
	global_store_dwordx4 v[166:167], v[224:227], off
	v_cvt_f32_ubyte0_e32 v216, v214
	v_cvt_f32_ubyte1_e32 v217, v214
	v_cvt_f32_ubyte2_e32 v218, v214
	v_cvt_f32_ubyte3_e32 v219, v214
	v_cvt_f32_ubyte0_e32 v220, v215
	v_cvt_f32_ubyte1_e32 v221, v215
	v_cvt_f32_ubyte2_e32 v222, v215
	v_cvt_f32_ubyte3_e32 v223, v215
	v_pk_mul_f32 v[216:217], v[216:217], s[26:27] op_sel_hi:[1,0]
	v_pk_mul_f32 v[218:219], v[218:219], s[26:27] op_sel_hi:[1,0]
	v_pk_mul_f32 v[220:221], v[220:221], s[26:27] op_sel_hi:[1,0]
	v_pk_mul_f32 v[222:223], v[222:223], s[26:27] op_sel_hi:[1,0]
	v_pk_mul_f32 v[6:7], v[6:7], v[216:217]
	v_pk_mul_f32 v[8:9], v[8:9], v[218:219]
	v_pk_mul_f32 v[2:3], v[2:3], v[220:221]
	v_pk_mul_f32 v[4:5], v[4:5], v[222:223]
	v_cvt_pk_bf16_f32 v228, v6, v7
	v_cvt_pk_bf16_f32 v229, v8, v9
	v_cvt_pk_bf16_f32 v230, v2, v3
	v_cvt_pk_bf16_f32 v231, v4, v5
	s_mov_b32 s46, 0x1e000
	v_lshl_add_u64 v[166:167], v[160:161], 0, s[46:47]
	global_store_dwordx4 v[166:167], v[228:231], off
	s_mov_b64 s[18:19], -1
	s_andn2_b64 vcc, exec, s[42:43]
	s_cbranch_vccnz .LBB0_128
	s_andn2_b64 vcc, exec, s[0:1]
	s_cbranch_vccnz .LBB0_127
	s_barrier
	s_branch .LBB0_127

; #define LAS __attribute__((address_space(3)))
; __device__ __forceinline__ unsigned pk2(float lo, float hi) { return pg8::cvt_pk_bf16(lo, hi); }
; __device__ __forceinline__ s16x4 ldtr(LAS const unsigned char* p) { return __builtin_bit_cast(s16x4, __builtin_amdgcn_ds_read_tr16_b64_v4i16((LAS s16x4*)p)); }
; __device__ __forceinline__ void phase_attn(LAS unsigned char* lds, const bf16_t* Z, const float* rel_bias, bf16_t* OG, float* LSE, int S, int tid, int lane, int wave, int G) {
;     ...
;         float m = -1e30f;
; #pragma unroll
;         for (int kt = 0; kt < 9; ++kt) m = fmaxf(fmaxf(m, fmaxf(sa[kt][0], sa[kt][1])), fmaxf(sa[kt][2], sa[kt][3]));
;         m = fmaxf(m, __shfl_xor(m, 16)); m = fmaxf(m, __shfl_xor(m, 32));
;         float sum = 0.f;
; #pragma unroll
;         for (int kt = 0; kt < 9; ++kt)
; #pragma unroll
;             for (int j = 0; j < 4; ++j) { const float p = __builtin_amdgcn_exp2f(sa[kt][j] - m); sa[kt][j] = p; sum += p; }
;         sum += __shfl_xor(sum, 16); sum += __shfl_xor(sum, 32);
;         bf16x8 pf[5];
; #pragma unroll
;         for (int ks = 0; ks < 5; ++ks) { const f32x4 p0 = sa[2 * ks]; const f32x4 p1 = ks < 4 ? sa[ks < 4 ? 2 * ks + 1 : 8] : (f32x4){0.f, 0.f, 0.f, 0.f};
;             u32x4 w; w.x = pk2(p0[0], p0[1]); w.y = pk2(p0[2], p0[3]); w.z = pk2(p1[0], p1[1]); w.w = pk2(p1[2], p1[3]);
;             pf[ks] = __builtin_bit_cast(bf16x8, w); }
;         f32x4 oa[8];
; #pragma unroll
;         for (int cc = 0; cc < 8; ++cc) oa[cc] = (f32x4){0.f, 0.f, 0.f, 0.f};
;         LAS const unsigned char* vimg = lds + 65536;
; #pragma unroll
;         for (int ks = 0; ks < 5; ++ks) {
;             const int r0 = w16 + 32 * ks + 4 * g4 + tq; int r1 = r0 + 16; r1 = r1 > 255 ? 255 : r1;
; #pragma unroll
;             for (int cc = 0; cc < 8; ++cc) {
;                 const s16x4 lo = ldtr(vimg + off_b(r0, 2 * cc + (tp >> 1)) + 8 * (tp & 1));
.LBB0_249:
	v_max_f32_e32 v38, v31, v31
	v_max_f32_e32 v39, v30, v30
	v_max_f32_e32 v38, v39, v38
	v_max_f32_e32 v39, v33, v33
	v_max_f32_e32 v40, v32, v32
	v_max_f32_e32 v39, v40, v39
	s_mov_b32 s1, 0xf149f2ca
	v_max3_f32 v38, v38, s1, v39
	v_max_f32_e32 v39, v27, v27
	v_max_f32_e32 v40, v26, v26
	v_max_f32_e32 v39, v40, v39
	v_max_f32_e32 v40, v29, v29
	v_max_f32_e32 v41, v28, v28
	v_max_f32_e32 v40, v41, v40
	v_max3_f32 v38, v38, v39, v40
	v_max_f32_e32 v39, v23, v23
	v_max_f32_e32 v40, v22, v22
	v_max_f32_e32 v39, v40, v39
	v_max_f32_e32 v40, v25, v25
	v_max_f32_e32 v41, v24, v24
	v_max_f32_e32 v40, v41, v40
	v_max3_f32 v38, v38, v39, v40
	v_max_f32_e32 v39, v19, v19
	v_max_f32_e32 v40, v18, v18
	v_max_f32_e32 v39, v40, v39
	v_max_f32_e32 v40, v21, v21
	v_max_f32_e32 v41, v20, v20
	v_max_f32_e32 v40, v41, v40
	v_max3_f32 v38, v38, v39, v40
	v_max_f32_e32 v39, v15, v15
	v_max_f32_e32 v40, v14, v14
	v_max_f32_e32 v39, v40, v39
	v_max_f32_e32 v40, v17, v17
	v_max_f32_e32 v41, v16, v16
	v_max_f32_e32 v40, v41, v40
	v_max3_f32 v38, v38, v39, v40
	v_max_f32_e32 v39, v11, v11
	v_max_f32_e32 v40, v10, v10
	v_max_f32_e32 v39, v40, v39
	v_max_f32_e32 v40, v13, v13
	v_max_f32_e32 v41, v12, v12
	v_max_f32_e32 v40, v41, v40
	v_max3_f32 v38, v38, v39, v40
	v_max_f32_e32 v39, v7, v7
	v_max_f32_e32 v40, v6, v6
	v_max_f32_e32 v39, v40, v39
	v_max_f32_e32 v40, v9, v9
	v_max_f32_e32 v41, v8, v8
	v_max_f32_e32 v40, v41, v40
	v_max3_f32 v38, v38, v39, v40
	v_max_f32_e32 v39, v3, v3
	v_max_f32_e32 v40, v2, v2
	v_max_f32_e32 v39, v40, v39
	v_max_f32_e32 v40, v5, v5
	v_max_f32_e32 v41, v4, v4
	v_max_f32_e32 v40, v41, v40
	v_max3_f32 v38, v38, v39, v40
	v_max_f32_e32 v39, v35, v35
	v_max_f32_e32 v40, v34, v34
	v_max_f32_e32 v39, v40, v39
	v_max_f32_e32 v40, v37, v37
	v_max_f32_e32 v41, v36, v36
	v_max_f32_e32 v40, v41, v40
	v_max3_f32 v38, v38, v39, v40
	ds_bpermute_b32 v39, v1, v38
	s_ashr_i32 s1, s0, 31
	s_lshl_b64 s[0:1], s[0:1], 14
	s_lshl_b32 s54, s67, 8
	s_waitcnt lgkmcnt(0)
	v_max_f32_e32 v39, v39, v39
	v_max_f32_e32 v38, v38, v39
	ds_bpermute_b32 v39, v51, v38
	s_waitcnt lgkmcnt(0)
	v_max_f32_e32 v39, v39, v39
	v_max_f32_e32 v38, v38, v39
	v_sub_f32_e32 v30, v30, v38
	v_exp_f32_e32 v30, v30
	v_sub_f32_e32 v31, v31, v38
	v_exp_f32_e32 v31, v31
	v_sub_f32_e32 v32, v32, v38
	v_exp_f32_e32 v32, v32
	v_sub_f32_e32 v33, v33, v38
	v_exp_f32_e32 v33, v33
	v_sub_f32_e32 v26, v26, v38
	v_add_f32_e32 v39, 0, v30
	v_exp_f32_e32 v26, v26
	v_sub_f32_e32 v27, v27, v38
	v_add_f32_e32 v39, v31, v39
	v_exp_f32_e32 v27, v27
	v_sub_f32_e32 v28, v28, v38
	v_add_f32_e32 v39, v32, v39
	v_exp_f32_e32 v28, v28
	v_sub_f32_e32 v29, v29, v38
	v_add_f32_e32 v39, v33, v39
	v_exp_f32_e32 v29, v29
	v_sub_f32_e32 v22, v22, v38
	v_add_f32_e32 v39, v26, v39
	v_exp_f32_e32 v40, v22
	v_add_f32_e32 v39, v27, v39
	v_add_f32_e32 v39, v28, v39
	v_add_f32_e32 v39, v29, v39
	v_sub_f32_e32 v23, v23, v38
	v_add_f32_e32 v22, v40, v39
	v_exp_f32_e32 v39, v23
	v_sub_f32_e32 v23, v24, v38
	v_exp_f32_e32 v24, v23
	v_sub_f32_e32 v23, v25, v38
	v_exp_f32_e32 v25, v23
	v_sub_f32_e32 v18, v18, v38
	v_exp_f32_e32 v41, v18
	v_sub_f32_e32 v19, v19, v38
	v_add_f32_e32 v22, v39, v22
	v_exp_f32_e32 v42, v19
	v_sub_f32_e32 v19, v20, v38
	v_add_f32_e32 v22, v24, v22
	v_exp_f32_e32 v43, v19
	v_sub_f32_e32 v19, v21, v38
	v_add_f32_e32 v22, v25, v22
	v_exp_f32_e32 v44, v19
	v_sub_f32_e32 v14, v14, v38
	v_add_f32_e32 v18, v41, v22
	v_exp_f32_e32 v45, v14
	v_sub_f32_e32 v15, v15, v38
	v_add_f32_e32 v18, v42, v18
	v_exp_f32_e32 v46, v15
	v_sub_f32_e32 v15, v16, v38
	v_add_f32_e32 v18, v43, v18
	v_exp_f32_e32 v47, v15
	v_sub_f32_e32 v15, v17, v38
	v_add_f32_e32 v18, v44, v18
	v_exp_f32_e32 v48, v15
	v_sub_f32_e32 v10, v10, v38
	v_add_f32_e32 v14, v45, v18
	v_exp_f32_e32 v49, v10
	v_sub_f32_e32 v11, v11, v38
	v_add_f32_e32 v14, v46, v14
	v_exp_f32_e32 v61, v11
	v_sub_f32_e32 v11, v12, v38
	v_add_f32_e32 v14, v47, v14
	v_exp_f32_e32 v150, v11
	v_sub_f32_e32 v11, v13, v38
	v_add_f32_e32 v14, v48, v14
	v_exp_f32_e32 v13, v11
	v_sub_f32_e32 v6, v6, v38
	v_add_f32_e32 v10, v49, v14
	v_exp_f32_e32 v6, v6
	v_sub_f32_e32 v7, v7, v38
	v_add_f32_e32 v10, v61, v10
	v_exp_f32_e32 v7, v7
	v_sub_f32_e32 v8, v8, v38
	v_add_f32_e32 v10, v150, v10
	v_exp_f32_e32 v8, v8
	v_sub_f32_e32 v9, v9, v38
	v_add_f32_e32 v10, v13, v10
	v_exp_f32_e32 v9, v9
	v_sub_f32_e32 v2, v2, v38
	v_add_f32_e32 v10, v6, v10
	v_exp_f32_e32 v2, v2
	v_sub_f32_e32 v3, v3, v38
	v_add_f32_e32 v10, v7, v10
	v_exp_f32_e32 v3, v3
	v_sub_f32_e32 v4, v4, v38
	v_add_f32_e32 v10, v8, v10
	v_exp_f32_e32 v4, v4
	v_sub_f32_e32 v5, v5, v38
	v_add_f32_e32 v10, v9, v10
	v_exp_f32_e32 v5, v5
	v_sub_f32_e32 v11, v34, v38
	v_add_f32_e32 v10, v2, v10
	v_exp_f32_e32 v34, v11
	v_sub_f32_e32 v11, v35, v38
	v_add_f32_e32 v10, v3, v10
	v_exp_f32_e32 v35, v11
	v_sub_f32_e32 v11, v36, v38
	v_add_f32_e32 v10, v4, v10
	v_exp_f32_e32 v36, v11
	v_sub_f32_e32 v11, v37, v38
	v_add_f32_e32 v10, v5, v10
	v_exp_f32_e32 v37, v11
	v_add_f32_e32 v10, v34, v10
	v_add_f32_e32 v10, v35, v10
	v_add_f32_e32 v10, v36, v10
	v_add_f32_e32 v10, v37, v10
	ds_bpermute_b32 v11, v1, v10
	v_cvt_pk_bf16_f32 v19, v32, v33
	v_cvt_pk_bf16_f32 v21, v28, v29
	v_cvt_pk_bf16_f32 v15, v24, v25
	v_cvt_pk_bf16_f32 v6, v6, v7
	v_cvt_pk_bf16_f32 v7, v8, v9
	v_cvt_pk_bf16_f32 v8, v2, v3
	v_cvt_pk_bf16_f32 v3, v36, v37
	v_add_u32_e32 v24, v72, v71
	v_add_u32_e32 v28, v72, v73
	v_add_u32_e32 v32, v72, v74
	v_add_u32_e32 v36, v72, v75
	v_cvt_pk_bf16_f32 v18, v30, v31
	v_cvt_pk_bf16_f32 v20, v26, v27
	v_cvt_pk_bf16_f32 v14, v40, v39
	v_cvt_pk_bf16_f32 v16, v41, v42
	v_cvt_pk_bf16_f32 v17, v43, v44
	v_cvt_pk_bf16_f32 v2, v34, v35
	ds_read_b64_tr_b16 v[24:25], v24
	ds_read_b64_tr_b16 v[26:27], v97 offset:4096
	ds_read_b64_tr_b16 v[28:29], v28
	ds_read_b64_tr_b16 v[30:31], v98 offset:4096
	ds_read_b64_tr_b16 v[32:33], v32
	ds_read_b64_tr_b16 v[34:35], v99 offset:4096
	ds_read_b64_tr_b16 v[40:41], v36
	ds_read_b64_tr_b16 v[42:43], v100 offset:4096
	v_add_u32_e32 v36, v72, v76
	s_waitcnt lgkmcnt(8)
; __device__ __forceinline__ s16x4 ldtr(LAS const unsigned char* p) { return __builtin_bit_cast(s16x4, __builtin_amdgcn_ds_read_tr16_b64_v4i16((LAS s16x4*)p)); }
; __device__ __forceinline__ void phase_attn(LAS unsigned char* lds, const bf16_t* Z, const float* rel_bias, bf16_t* OG, float* LSE, int S, int tid, int lane, int wave, int G) {
;     ...
; #pragma unroll
;         for (int ks = 0; ks < 5; ++ks) {
;             const int r0 = w16 + 32 * ks + 4 * g4 + tq; int r1 = r0 + 16; r1 = r1 > 255 ? 255 : r1;
; #pragma unroll
;             for (int cc = 0; cc < 8; ++cc) {
;                 const s16x4 lo = ldtr(vimg + off_b(r0, 2 * cc + (tp >> 1)) + 8 * (tp & 1));
;                 const s16x4 hi = ldtr(vimg + off_b(r1, 2 * cc + (tp >> 1)) + 8 * (tp & 1));
;                 const bf16x8 vf = (bf16x8){lo[0], lo[1], lo[2], lo[3], hi[0], hi[1], hi[2], hi[3]};
;                 oa[cc] = __builtin_amdgcn_mfma_f32_16x16x32_bf16(vf, pf[ks], oa[cc], 0, 0, 0);
;             }
;         }
	v_add_f32_e32 v22, v10, v11
	v_cvt_pk_bf16_f32 v10, v45, v46
	v_cvt_pk_bf16_f32 v11, v47, v48
	ds_read_b64_tr_b16 v[44:45], v36
	ds_read_b64_tr_b16 v[46:47], v101 offset:4096
	v_add_u32_e32 v36, v72, v77
	v_cvt_pk_bf16_f32 v13, v150, v13
	ds_read_b64_tr_b16 v[150:151], v36
	ds_read_b64_tr_b16 v[152:153], v102 offset:4096
	v_add_u32_e32 v36, v72, v78
	ds_read_b64_tr_b16 v[154:155], v36
	ds_read_b64_tr_b16 v[156:157], v104 offset:4096
	v_add_u32_e32 v36, v72, v79
	ds_read_b64_tr_b16 v[158:159], v36
	ds_read_b64_tr_b16 v[160:161], v105 offset:4096
	v_add_u32_e32 v36, v80, v71
	s_waitcnt lgkmcnt(14)
	v_mfma_f32_16x16x32_bf16 v[24:27], v[24:27], v[18:21], 0
	v_cvt_pk_bf16_f32 v12, v49, v61
	v_cvt_pk_bf16_f32 v9, v4, v5
	v_mov_b32_e32 v4, v0
	s_waitcnt lgkmcnt(12)
	v_mfma_f32_16x16x32_bf16 v[28:31], v[28:31], v[18:21], 0
	v_mov_b32_e32 v5, v0
	ds_bpermute_b32 v23, v51, v22
	s_waitcnt lgkmcnt(11)
	v_mfma_f32_16x16x32_bf16 v[32:35], v[32:35], v[18:21], 0
	s_waitcnt lgkmcnt(9)
	v_mfma_f32_16x16x32_bf16 v[40:43], v[40:43], v[18:21], 0
	s_waitcnt lgkmcnt(7)
	v_mfma_f32_16x16x32_bf16 v[44:47], v[44:47], v[18:21], 0
	s_waitcnt lgkmcnt(5)
	v_mfma_f32_16x16x32_bf16 v[150:153], v[150:153], v[18:21], 0
	s_waitcnt lgkmcnt(3)
	v_mfma_f32_16x16x32_bf16 v[154:157], v[154:157], v[18:21], 0
	s_waitcnt lgkmcnt(1)
	v_mfma_f32_16x16x32_bf16 v[18:21], v[158:161], v[18:21], 0
	ds_read_b64_tr_b16 v[204:205], v36
	ds_read_b64_tr_b16 v[206:207], v106 offset:4096
	v_add_u32_e32 v221, v80, v73
	ds_read_b64_tr_b16 v[208:209], v221
	ds_read_b64_tr_b16 v[210:211], v107 offset:4096
	v_add_u32_e32 v222, v80, v74
	ds_read_b64_tr_b16 v[212:213], v222
	ds_read_b64_tr_b16 v[214:215], v108 offset:4096
	s_waitcnt lgkmcnt(4)
	v_mfma_f32_16x16x32_bf16 v[24:27], v[204:207], v[14:17], v[24:27]
	v_add_u32_e32 v223, v80, v75
	ds_read_b64_tr_b16 v[216:217], v223
	ds_read_b64_tr_b16 v[218:219], v109 offset:4096
	s_waitcnt lgkmcnt(4)
	v_mfma_f32_16x16x32_bf16 v[28:31], v[208:211], v[14:17], v[28:31]
	v_add_u32_e32 v220, v80, v76
	ds_read_b64_tr_b16 v[204:205], v220
	ds_read_b64_tr_b16 v[206:207], v110 offset:4096
	s_waitcnt lgkmcnt(4)
	v_mfma_f32_16x16x32_bf16 v[32:35], v[212:215], v[14:17], v[32:35]
	v_add_u32_e32 v221, v80, v77
	ds_read_b64_tr_b16 v[208:209], v221
	ds_read_b64_tr_b16 v[210:211], v111 offset:4096
	s_waitcnt lgkmcnt(4)
	v_mfma_f32_16x16x32_bf16 v[40:43], v[216:219], v[14:17], v[40:43]
	v_add_u32_e32 v222, v80, v78
	ds_read_b64_tr_b16 v[212:213], v222
	ds_read_b64_tr_b16 v[214:215], v112 offset:4096
	s_waitcnt lgkmcnt(4)
	v_mfma_f32_16x16x32_bf16 v[44:47], v[204:207], v[14:17], v[44:47]
	v_add_u32_e32 v223, v80, v79
	ds_read_b64_tr_b16 v[216:217], v223
	ds_read_b64_tr_b16 v[218:219], v113 offset:4096
	s_waitcnt lgkmcnt(4)
	v_mfma_f32_16x16x32_bf16 v[150:153], v[208:211], v[14:17], v[150:153]
	v_add_u32_e32 v220, v81, v71
	ds_read_b64_tr_b16 v[204:205], v220
	ds_read_b64_tr_b16 v[206:207], v114 offset:4096
	s_waitcnt lgkmcnt(4)
	v_mfma_f32_16x16x32_bf16 v[154:157], v[212:215], v[14:17], v[154:157]
	v_add_u32_e32 v221, v81, v73
	ds_read_b64_tr_b16 v[208:209], v221
	ds_read_b64_tr_b16 v[210:211], v115 offset:4096
	s_waitcnt lgkmcnt(4)
	v_mfma_f32_16x16x32_bf16 v[14:17], v[216:219], v[14:17], v[18:21]
	v_add_u32_e32 v222, v81, v74
	ds_read_b64_tr_b16 v[212:213], v222
	ds_read_b64_tr_b16 v[214:215], v116 offset:4096
	s_waitcnt lgkmcnt(4)
	v_mfma_f32_16x16x32_bf16 v[18:21], v[204:207], v[10:13], v[24:27]
	v_add_u32_e32 v223, v81, v75
	ds_read_b64_tr_b16 v[216:217], v223
	ds_read_b64_tr_b16 v[218:219], v117 offset:4096
	s_waitcnt lgkmcnt(4)
	v_mfma_f32_16x16x32_bf16 v[24:27], v[208:211], v[10:13], v[28:31]
	v_add_u32_e32 v220, v81, v76
	ds_read_b64_tr_b16 v[204:205], v220
	ds_read_b64_tr_b16 v[206:207], v118 offset:4096
	s_waitcnt lgkmcnt(4)
	v_mfma_f32_16x16x32_bf16 v[28:31], v[212:215], v[10:13], v[32:35]
	v_add_u32_e32 v221, v81, v77
	ds_read_b64_tr_b16 v[208:209], v221
	ds_read_b64_tr_b16 v[210:211], v119 offset:4096
	s_waitcnt lgkmcnt(4)
	v_mfma_f32_16x16x32_bf16 v[32:35], v[216:219], v[10:13], v[40:43]
	v_add_u32_e32 v222, v81, v78
	ds_read_b64_tr_b16 v[212:213], v222
	ds_read_b64_tr_b16 v[214:215], v120 offset:4096
	s_waitcnt lgkmcnt(4)
	v_mfma_f32_16x16x32_bf16 v[40:43], v[204:207], v[10:13], v[44:47]
	v_add_u32_e32 v223, v81, v79
	ds_read_b64_tr_b16 v[216:217], v223
	ds_read_b64_tr_b16 v[218:219], v121 offset:4096
	s_waitcnt lgkmcnt(4)
	v_mfma_f32_16x16x32_bf16 v[44:47], v[208:211], v[10:13], v[150:153]
	v_add_u32_e32 v220, v82, v71
	ds_read_b64_tr_b16 v[204:205], v220
	ds_read_b64_tr_b16 v[206:207], v122 offset:4096
	s_waitcnt lgkmcnt(4)
	v_mfma_f32_16x16x32_bf16 v[150:153], v[212:215], v[10:13], v[154:157]
	v_add_u32_e32 v221, v82, v73
	ds_read_b64_tr_b16 v[208:209], v221
	ds_read_b64_tr_b16 v[210:211], v123 offset:4096
	s_waitcnt lgkmcnt(4)
	v_mfma_f32_16x16x32_bf16 v[10:13], v[216:219], v[10:13], v[14:17]
	v_add_u32_e32 v222, v82, v74
	ds_read_b64_tr_b16 v[212:213], v222
	ds_read_b64_tr_b16 v[214:215], v124 offset:4096
	s_waitcnt lgkmcnt(4)
	v_mfma_f32_16x16x32_bf16 v[14:17], v[204:207], v[6:9], v[18:21]
	v_add_u32_e32 v223, v82, v75
	ds_read_b64_tr_b16 v[216:217], v223
	ds_read_b64_tr_b16 v[218:219], v125 offset:4096
	s_waitcnt lgkmcnt(4)
	v_mfma_f32_16x16x32_bf16 v[18:21], v[208:211], v[6:9], v[24:27]
	v_add_u32_e32 v220, v82, v76
	ds_read_b64_tr_b16 v[204:205], v220
	ds_read_b64_tr_b16 v[206:207], v126 offset:4096
	s_waitcnt lgkmcnt(4)
; __device__ __forceinline__ unsigned pk2(float lo, float hi) { return pg8::cvt_pk_bf16(lo, hi); }
; __device__ __forceinline__ s16x4 ldtr(LAS const unsigned char* p) { return __builtin_bit_cast(s16x4, __builtin_amdgcn_ds_read_tr16_b64_v4i16((LAS s16x4*)p)); }
; __device__ __forceinline__ void phase_attn(LAS unsigned char* lds, const bf16_t* Z, const float* rel_bias, bf16_t* OG, float* LSE, int S, int tid, int lane, int wave, int G) {
;     ...
; #pragma unroll
;         for (int ks = 0; ks < 5; ++ks) {
;             const int r0 = w16 + 32 * ks + 4 * g4 + tq; int r1 = r0 + 16; r1 = r1 > 255 ? 255 : r1;
; #pragma unroll
;             for (int cc = 0; cc < 8; ++cc) {
;                 const s16x4 lo = ldtr(vimg + off_b(r0, 2 * cc + (tp >> 1)) + 8 * (tp & 1));
;                 const s16x4 hi = ldtr(vimg + off_b(r1, 2 * cc + (tp >> 1)) + 8 * (tp & 1));
;                 const bf16x8 vf = (bf16x8){lo[0], lo[1], lo[2], lo[3], hi[0], hi[1], hi[2], hi[3]};
;                 oa[cc] = __builtin_amdgcn_mfma_f32_16x16x32_bf16(vf, pf[ks], oa[cc], 0, 0, 0);
;             }
;         }
;         {
;             const float inv = 1.0f / sum;
;             const size_t row = rowbase + ((size_t)(q0 + c) << sh);
;             bf16_t* op = OG + ((size_t)grp * CH + row) * AW + h * 128 + 4 * g4;
; #pragma unroll
;             for (int cc = 0; cc < 8; ++cc) { const f32x4 o = oa[cc] * inv; u32x2 w; w.x = pk2(o[0], o[1]); w.y = pk2(o[2], o[3]); *(u32x2*)(op + 16 * cc) = w; }
;             if (g4 == 0) LSE[((size_t)grp * CH + row) * 4 + h] = m + log2f(sum);
;         }
	v_mfma_f32_16x16x32_bf16 v[24:27], v[212:215], v[6:9], v[28:31]
	v_add_u32_e32 v221, v82, v77
	ds_read_b64_tr_b16 v[208:209], v221
	ds_read_b64_tr_b16 v[210:211], v127 offset:4096
	s_waitcnt lgkmcnt(4)
	v_mfma_f32_16x16x32_bf16 v[28:31], v[216:219], v[6:9], v[32:35]
	v_add_u32_e32 v222, v82, v78
	ds_read_b64_tr_b16 v[212:213], v222
	ds_read_b64_tr_b16 v[214:215], v128 offset:4096
	s_waitcnt lgkmcnt(4)
	v_mfma_f32_16x16x32_bf16 v[32:35], v[204:207], v[6:9], v[40:43]
	v_add_u32_e32 v223, v82, v79
	ds_read_b64_tr_b16 v[216:217], v223
	ds_read_b64_tr_b16 v[218:219], v129 offset:4096
	s_waitcnt lgkmcnt(4)
	v_mfma_f32_16x16x32_bf16 v[40:43], v[208:211], v[6:9], v[44:47]
	v_add_u32_e32 v220, v83, v71
	ds_read_b64_tr_b16 v[204:205], v220
	ds_read_b64_tr_b16 v[206:207], v142 offset:4096
	s_waitcnt lgkmcnt(4)
	v_mfma_f32_16x16x32_bf16 v[44:47], v[212:215], v[6:9], v[150:153]
	v_add_u32_e32 v221, v83, v73
	ds_read_b64_tr_b16 v[208:209], v221
	ds_read_b64_tr_b16 v[210:211], v143 offset:4096
	s_waitcnt lgkmcnt(4)
	v_mfma_f32_16x16x32_bf16 v[6:9], v[216:219], v[6:9], v[10:13]
	v_add_u32_e32 v222, v83, v74
	ds_read_b64_tr_b16 v[212:213], v222
	ds_read_b64_tr_b16 v[214:215], v144 offset:4096
	s_waitcnt lgkmcnt(4)
	v_mfma_f32_16x16x32_bf16 v[10:13], v[204:207], v[2:5], v[14:17]
	v_add_u32_e32 v223, v83, v75
	ds_read_b64_tr_b16 v[216:217], v223
	ds_read_b64_tr_b16 v[218:219], v145 offset:4096
	s_waitcnt lgkmcnt(4)
	v_mfma_f32_16x16x32_bf16 v[14:17], v[208:211], v[2:5], v[18:21]
	v_add_u32_e32 v220, v83, v76
	ds_read_b64_tr_b16 v[204:205], v220
	ds_read_b64_tr_b16 v[206:207], v146 offset:4096
	s_waitcnt lgkmcnt(4)
	v_mfma_f32_16x16x32_bf16 v[18:21], v[212:215], v[2:5], v[24:27]
	v_add_u32_e32 v221, v83, v77
	ds_read_b64_tr_b16 v[208:209], v221
	ds_read_b64_tr_b16 v[210:211], v147 offset:4096
	s_waitcnt lgkmcnt(4)
	v_mfma_f32_16x16x32_bf16 v[24:27], v[216:219], v[2:5], v[28:31]
	v_add_u32_e32 v222, v83, v78
	ds_read_b64_tr_b16 v[212:213], v222
	ds_read_b64_tr_b16 v[214:215], v148 offset:4096
	s_waitcnt lgkmcnt(4)
	v_mfma_f32_16x16x32_bf16 v[28:31], v[204:207], v[2:5], v[32:35]
	v_add_u32_e32 v223, v83, v79
	ds_read_b64_tr_b16 v[216:217], v223
	ds_read_b64_tr_b16 v[218:219], v149 offset:4096
	s_waitcnt lgkmcnt(4)
	v_mfma_f32_16x16x32_bf16 v[32:35], v[208:211], v[2:5], v[40:43]
	s_waitcnt lgkmcnt(2)
	v_mfma_f32_16x16x32_bf16 v[40:43], v[212:215], v[2:5], v[44:47]
	s_waitcnt lgkmcnt(0)
	v_mfma_f32_16x16x32_bf16 v[6:9], v[216:219], v[2:5], v[6:9]
	v_add_f32_e32 v4, v22, v23
	v_div_scale_f32 v2, s[4:5], v4, v4, 1.0
	v_rcp_f32_e32 v3, v2
	v_lshlrev_b32_e32 v44, 1, v50
	v_mov_b32_e32 v45, v0
	v_fma_f32 v5, -v2, v3, 1.0
	v_fmac_f32_e32 v3, v5, v3
	v_div_scale_f32 v5, vcc, 1.0, v4, 1.0
	v_mul_f32_e32 v22, v5, v3
	v_fma_f32 v23, -v2, v22, v5
	v_fmac_f32_e32 v22, v23, v3
	v_fma_f32 v2, -v2, v22, v5
	v_div_fmas_f32 v2, v2, v3, v22
	v_div_fixup_f32 v22, v2, v4, 1.0
	v_lshl_add_u64 v[2:3], v[62:63], 0, s[0:1]
	v_lshlrev_b64 v[36:37], 10, v[2:3]
	v_lshl_add_u64 v[36:37], s[8:9], 0, v[36:37]
	v_lshl_add_u64 v[36:37], v[36:37], 0, s[54:55]
	v_pk_mul_f32 v[12:13], v[22:23], v[12:13] op_sel_hi:[0,1]
	v_pk_mul_f32 v[10:11], v[22:23], v[10:11] op_sel_hi:[0,1]
	v_lshl_add_u64 v[36:37], v[36:37], 0, v[44:45]
	v_cvt_pk_bf16_f32 v10, v10, v11
	v_cvt_pk_bf16_f32 v11, v12, v13
	global_store_dwordx2 v[36:37], v[10:11], off
	v_pk_mul_f32 v[10:11], v[22:23], v[16:17] op_sel_hi:[0,1]
	v_pk_mul_f32 v[12:13], v[22:23], v[14:15] op_sel_hi:[0,1]
	v_cvt_pk_bf16_f32 v12, v12, v13
	v_cvt_pk_bf16_f32 v13, v10, v11
	global_store_dwordx2 v[36:37], v[12:13], off offset:32
	v_pk_mul_f32 v[10:11], v[22:23], v[20:21] op_sel_hi:[0,1]
	v_pk_mul_f32 v[12:13], v[22:23], v[18:19] op_sel_hi:[0,1]
	v_cvt_pk_bf16_f32 v12, v12, v13
	v_cvt_pk_bf16_f32 v13, v10, v11
	global_store_dwordx2 v[36:37], v[12:13], off offset:64
	v_pk_mul_f32 v[10:11], v[22:23], v[26:27] op_sel_hi:[0,1]
	v_pk_mul_f32 v[12:13], v[22:23], v[24:25] op_sel_hi:[0,1]
	v_cvt_pk_bf16_f32 v12, v12, v13
	v_cvt_pk_bf16_f32 v13, v10, v11
	global_store_dwordx2 v[36:37], v[12:13], off offset:96
	v_pk_mul_f32 v[10:11], v[22:23], v[30:31] op_sel_hi:[0,1]
	v_pk_mul_f32 v[12:13], v[22:23], v[28:29] op_sel_hi:[0,1]
	v_cvt_pk_bf16_f32 v12, v12, v13
	v_cvt_pk_bf16_f32 v13, v10, v11
	global_store_dwordx2 v[36:37], v[12:13], off offset:128
	v_pk_mul_f32 v[10:11], v[22:23], v[34:35] op_sel_hi:[0,1]
	v_pk_mul_f32 v[12:13], v[22:23], v[32:33] op_sel_hi:[0,1]
	v_cvt_pk_bf16_f32 v12, v12, v13
	v_cvt_pk_bf16_f32 v13, v10, v11
	global_store_dwordx2 v[36:37], v[12:13], off offset:160
	v_pk_mul_f32 v[10:11], v[22:23], v[42:43] op_sel_hi:[0,1]
	v_pk_mul_f32 v[12:13], v[22:23], v[40:41] op_sel_hi:[0,1]
	v_pk_mul_f32 v[8:9], v[22:23], v[8:9] op_sel_hi:[0,1]
	v_pk_mul_f32 v[6:7], v[22:23], v[6:7] op_sel_hi:[0,1]
	v_cvt_pk_bf16_f32 v12, v12, v13
	v_cvt_pk_bf16_f32 v13, v10, v11
	v_cvt_pk_bf16_f32 v6, v6, v7
	v_cvt_pk_bf16_f32 v7, v8, v9
	global_store_dwordx2 v[36:37], v[12:13], off offset:192
	global_store_dwordx2 v[36:37], v[6:7], off offset:224
	s_and_saveexec_b64 s[0:1], s[40:41]
	s_cbranch_execz .LBB0_246
	s_mov_b32 s4, 0x800000
	v_cmp_gt_f32_e32 vcc, s4, v4
	v_lshl_add_u64 v[2:3], v[2:3], 4, s[6:7]
	s_lshl_b32 s54, s67, 2
	v_cndmask_b32_e64 v6, 0, 32, vcc
	v_ldexp_f32 v4, v4, v6
	v_log_f32_e32 v4, v4
	v_cndmask_b32_e32 v5, 0, v201, vcc
	v_lshl_add_u64 v[2:3], v[2:3], 0, s[54:55]
	v_sub_f32_e32 v4, v4, v5
	v_add_f32_e32 v4, v38, v4
	global_store_dword v[2:3], v4, off
	s_branch .LBB0_246
